# stack: EpiGate + MLA VALU rowsum + rope sw-pipelined loop + EpiRowScale (uq,uk) hoisted loads + skinny meta loads hoisted
# speedup vs baseline: 1.0138x; 1.0071x over previous
.LBB0_241:
	s_and_b32 s5, s4, 0x70
	s_and_b32 s8, s6, 0xffffff00
	s_or_b32 s5, s5, s8
	v_or_b32_e32 v10, s5, v6
	v_ashrrev_i32_e32 v11, 31, v10
	v_lshlrev_b64 v[10:11], 11, v[10:11]
	v_lshl_add_u64 v[34:35], v[0:1], 0, v[10:11]
	s_mov_b32 s5, 0x40000
	v_add_co_u32_e32 v36, vcc, s5, v34
	global_load_dwordx4 v[64:67], v[2:3], off offset:1024
	global_load_dwordx4 v[80:83], v[34:35], off
	v_addc_co_u32_e32 v37, vcc, 0, v35, vcc
	global_load_dwordx4 v[96:99], v[36:37], off
	global_load_dwordx4 v[68:71], v[2:3], off offset:1088
	global_load_dwordx4 v[84:87], v[34:35], off offset:64
	global_load_dwordx4 v[100:103], v[36:37], off offset:64
	global_load_dwordx4 v[72:75], v[2:3], off offset:1152
	global_load_dwordx4 v[88:91], v[34:35], off offset:128
	global_load_dwordx4 v[104:107], v[36:37], off offset:128
	global_load_dwordx4 v[76:79], v[2:3], off offset:1216
	global_load_dwordx4 v[92:95], v[34:35], off offset:192
	global_load_dwordx4 v[108:111], v[36:37], off offset:192
	s_andn2_b64 vcc, exec, s[2:3]
	s_waitcnt vmcnt(10)
	v_mfma_f32_16x16x32_bf16 v[14:17], v[80:83], v[64:67], 0
	s_waitcnt vmcnt(9)
	v_mfma_f32_16x16x32_bf16 v[10:13], v[96:99], v[64:67], 0
	s_waitcnt vmcnt(7)
	v_mfma_f32_16x16x32_bf16 v[14:17], v[84:87], v[68:71], v[14:17]
	s_waitcnt vmcnt(6)
	v_mfma_f32_16x16x32_bf16 v[10:13], v[100:103], v[68:71], v[10:13]
	s_waitcnt vmcnt(4)
	v_mfma_f32_16x16x32_bf16 v[14:17], v[88:91], v[72:75], v[14:17]
	s_waitcnt vmcnt(3)
	v_mfma_f32_16x16x32_bf16 v[10:13], v[104:107], v[72:75], v[10:13]
	s_waitcnt vmcnt(1)
	v_mfma_f32_16x16x32_bf16 v[14:17], v[92:95], v[76:79], v[14:17]
	s_waitcnt vmcnt(0)
	v_mfma_f32_16x16x32_bf16 v[10:13], v[108:111], v[76:79], v[10:13]
	s_nop 5
	ds_write_b128 v8, v[14:17]
	s_nop 1
	ds_write_b128 v8, v[10:13] offset:1024
	s_waitcnt lgkmcnt(0)
	s_barrier
	s_cbranch_vccnz .LBB0_240
	ds_read_b128 v[10:13], v7 offset:2048
	ds_read_b128 v[14:17], v7
	ds_read_b128 v[18:21], v7 offset:1024
	ds_read_b128 v[22:25], v7 offset:3072
	ds_read_b128 v[26:29], v7 offset:4096
	s_ashr_i32 s5, s4, 31
	s_waitcnt lgkmcnt(3)
	v_pk_add_f32 v[16:17], v[16:17], v[12:13]
	v_pk_add_f32 v[30:31], v[14:15], v[10:11]
	ds_read_b128 v[10:13], v7 offset:5120
	s_waitcnt lgkmcnt(2)
	v_pk_add_f32 v[20:21], v[20:21], v[24:25]
	s_waitcnt lgkmcnt(1)
	v_pk_add_f32 v[24:25], v[16:17], v[28:29]
	ds_read_b128 v[14:17], v7 offset:6144
	v_pk_add_f32 v[22:23], v[18:19], v[22:23]
	v_pk_add_f32 v[26:27], v[30:31], v[26:27]
	s_waitcnt lgkmcnt(1)
	v_pk_add_f32 v[28:29], v[20:21], v[12:13]
	ds_read_b128 v[18:21], v7 offset:7168
	v_pk_add_f32 v[22:23], v[22:23], v[10:11]
	s_waitcnt lgkmcnt(1)
	v_pk_add_f32 v[24:25], v[24:25], v[16:17]
	ds_read_b128 v[10:13], v7 offset:8192
	v_pk_add_f32 v[26:27], v[26:27], v[14:15]
	ds_read_b128 v[14:17], v7 offset:9216
	s_waitcnt lgkmcnt(2)
	v_pk_add_f32 v[28:29], v[28:29], v[20:21]
	v_pk_add_f32 v[22:23], v[22:23], v[18:19]
	ds_read_b128 v[18:21], v7 offset:10240
	s_waitcnt lgkmcnt(2)
	v_pk_add_f32 v[24:25], v[24:25], v[12:13]
	v_pk_add_f32 v[26:27], v[26:27], v[10:11]
	s_waitcnt lgkmcnt(1)
	v_pk_add_f32 v[28:29], v[28:29], v[16:17]
	ds_read_b128 v[10:13], v7 offset:11264
	v_pk_add_f32 v[22:23], v[22:23], v[14:15]
	ds_read_b128 v[14:17], v7 offset:12288
	s_waitcnt lgkmcnt(2)
	v_pk_add_f32 v[20:21], v[24:25], v[20:21]
	v_pk_add_f32 v[24:25], v[26:27], v[18:19]
	s_waitcnt lgkmcnt(1)
	v_pk_add_f32 v[26:27], v[28:29], v[12:13]
	v_pk_add_f32 v[28:29], v[22:23], v[10:11]
	ds_read_b128 v[10:13], v7 offset:13312
	s_waitcnt lgkmcnt(1)
	v_pk_add_f32 v[30:31], v[20:21], v[16:17]
	ds_read_b128 v[16:19], v7 offset:14336
	v_pk_add_f32 v[14:15], v[24:25], v[14:15]
	ds_read_b128 v[20:23], v7 offset:15360
	s_waitcnt lgkmcnt(2)
	v_pk_add_f32 v[10:11], v[28:29], v[10:11]
	v_pk_add_f32 v[12:13], v[26:27], v[12:13]
	s_waitcnt lgkmcnt(1)
	v_pk_add_f32 v[14:15], v[14:15], v[16:17]
	v_pk_add_f32 v[18:19], v[30:31], v[18:19]
	v_mul_f32_e32 v9, 0xbfb8aa3b, v14
	v_exp_f32_e32 v9, v9
	v_mul_f32_e32 v16, 0xbfb8aa3b, v15
	v_exp_f32_e32 v17, v16
	s_waitcnt lgkmcnt(0)
	v_pk_add_f32 v[10:11], v[10:11], v[20:21]
	v_add_f32_e32 v9, 1.0, v9
	v_rcp_f32_e32 v16, v9
	v_add_f32_e32 v9, 1.0, v17
	v_mul_f32_e32 v17, 0xbfb8aa3b, v18
	v_exp_f32_e32 v20, v17
	v_mul_f32_e32 v17, 0xbfb8aa3b, v19
	v_exp_f32_e32 v21, v17
	v_rcp_f32_e32 v17, v9
	v_add_f32_e32 v9, 1.0, v20
	v_rcp_f32_e32 v20, v9
	v_add_f32_e32 v9, 1.0, v21
	v_rcp_f32_e32 v21, v9
	v_pk_mul_f32 v[14:15], v[14:15], v[16:17]
	v_pk_add_f32 v[12:13], v[12:13], v[22:23]
	v_pk_mul_f32 v[10:11], v[10:11], v[14:15]
	v_pk_mul_f32 v[14:15], v[18:19], v[20:21]
	v_cvt_pk_bf16_f32 v10, v10, v11
	v_pk_mul_f32 v[12:13], v[12:13], v[14:15]
	s_nop 0
	v_cvt_pk_bf16_f32 v11, v12, v13
	v_lshl_add_u64 v[12:13], s[4:5], 1, v[4:5]
	global_store_dwordx2 v[12:13], v[10:11], off
	s_branch .LBB0_240

.LBB0_338:
	v_add_u32_e32 v9, s10, v6
	v_mad_i64_i32 v[22:23], s[18:19], v9, s31, v[2:3]
	global_load_dwordx4 v[64:67], v[0:1], off
	global_load_dwordx4 v[152:155], v[22:23], off
	global_load_dwordx4 v[68:71], v[0:1], off offset:64
	global_load_dwordx4 v[156:159], v[22:23], off offset:64
	global_load_dwordx4 v[72:75], v[0:1], off offset:128
	global_load_dwordx4 v[160:163], v[22:23], off offset:128
	global_load_dwordx4 v[76:79], v[0:1], off offset:192
	global_load_dwordx4 v[164:167], v[22:23], off offset:192
	global_load_dwordx4 v[80:83], v[0:1], off offset:256
	global_load_dwordx4 v[168:171], v[22:23], off offset:256
	global_load_dwordx4 v[84:87], v[0:1], off offset:320
	global_load_dwordx4 v[172:175], v[22:23], off offset:320
	global_load_dwordx4 v[88:91], v[0:1], off offset:384
	global_load_dwordx4 v[176:179], v[22:23], off offset:384
	global_load_dwordx4 v[92:95], v[0:1], off offset:448
	global_load_dwordx4 v[180:183], v[22:23], off offset:448
	global_load_dwordx4 v[96:99], v[0:1], off offset:512
	global_load_dwordx4 v[184:187], v[22:23], off offset:512
	global_load_dwordx4 v[100:103], v[0:1], off offset:576
	global_load_dwordx4 v[188:191], v[22:23], off offset:576
	global_load_dwordx4 v[104:107], v[0:1], off offset:640
	global_load_dwordx4 v[192:195], v[22:23], off offset:640
	s_andn2_b64 vcc, exec, s[4:5]
	s_waitcnt vmcnt(20)
	v_mfma_f32_16x16x32_bf16 v[10:13], v[152:155], v[64:67], 0
	s_waitcnt vmcnt(18)
	v_mfma_f32_16x16x32_bf16 v[10:13], v[156:159], v[68:71], v[10:13]
	s_waitcnt vmcnt(16)
	v_mfma_f32_16x16x32_bf16 v[10:13], v[160:163], v[72:75], v[10:13]
	s_waitcnt vmcnt(14)
	v_mfma_f32_16x16x32_bf16 v[10:13], v[164:167], v[76:79], v[10:13]
	s_waitcnt vmcnt(12)
	v_mfma_f32_16x16x32_bf16 v[10:13], v[168:171], v[80:83], v[10:13]
	s_waitcnt vmcnt(10)
	v_mfma_f32_16x16x32_bf16 v[10:13], v[172:175], v[84:87], v[10:13]
	s_waitcnt vmcnt(8)
	v_mfma_f32_16x16x32_bf16 v[10:13], v[176:179], v[88:91], v[10:13]
	s_waitcnt vmcnt(6)
	v_mfma_f32_16x16x32_bf16 v[10:13], v[180:183], v[92:95], v[10:13]
	s_waitcnt vmcnt(4)
	v_mfma_f32_16x16x32_bf16 v[10:13], v[184:187], v[96:99], v[10:13]
	s_waitcnt vmcnt(2)
	v_mfma_f32_16x16x32_bf16 v[10:13], v[188:191], v[100:103], v[10:13]
	s_waitcnt vmcnt(0)
	v_mfma_f32_16x16x32_bf16 v[10:13], v[192:195], v[104:107], v[10:13]
	s_nop 7
	ds_write_b128 v8, v[10:13]
	s_waitcnt lgkmcnt(0)
	s_barrier
	s_cbranch_vccnz .LBB0_337
	ds_read_b128 v[10:13], v7
	ds_read_b128 v[14:17], v7 offset:1024
	s_load_dwordx2 s[18:19], s[80:81], 0x8
	s_ashr_i32 s11, s10, 31
	v_lshl_add_u64 v[18:19], v[148:149], 0, s[10:11]
	v_lshlrev_b64 v[20:21], 2, v[18:19]
	s_waitcnt lgkmcnt(0)
	v_pk_add_f32 v[16:17], v[12:13], v[16:17]
	v_pk_add_f32 v[14:15], v[10:11], v[14:15]
	ds_read_b128 v[10:13], v7 offset:2048
	s_waitcnt lgkmcnt(0)
	v_pk_add_f32 v[16:17], v[16:17], v[12:13]
	v_pk_add_f32 v[14:15], v[14:15], v[10:11]
	ds_read_b128 v[10:13], v7 offset:3072
	s_waitcnt lgkmcnt(0)
	v_pk_add_f32 v[16:17], v[16:17], v[12:13]
	v_pk_add_f32 v[14:15], v[14:15], v[10:11]
	ds_read_b128 v[10:13], v7 offset:4096
	s_waitcnt lgkmcnt(0)
	v_pk_add_f32 v[16:17], v[16:17], v[12:13]
	v_pk_add_f32 v[14:15], v[14:15], v[10:11]
	ds_read_b128 v[10:13], v7 offset:5120
	s_waitcnt lgkmcnt(0)
	v_pk_add_f32 v[16:17], v[16:17], v[12:13]
	v_pk_add_f32 v[14:15], v[14:15], v[10:11]
	ds_read_b128 v[10:13], v7 offset:6144
	s_waitcnt lgkmcnt(0)
	v_pk_add_f32 v[16:17], v[16:17], v[12:13]
	v_pk_add_f32 v[14:15], v[14:15], v[10:11]
	ds_read_b128 v[10:13], v7 offset:7168
	s_waitcnt lgkmcnt(0)
	v_pk_add_f32 v[14:15], v[14:15], v[10:11]
	v_lshl_add_u64 v[10:11], s[18:19], 0, v[20:21]
	v_pk_add_f32 v[16:17], v[16:17], v[12:13]
	global_load_dwordx4 v[10:13], v[10:11], off
	s_waitcnt vmcnt(0)
	v_pk_fma_f32 v[10:11], v[14:15], 0.5, v[10:11] op_sel_hi:[1,0,1]
	v_pk_fma_f32 v[12:13], v[16:17], 0.5, v[12:13] op_sel_hi:[1,0,1]
	v_lshl_add_u64 v[14:15], s[6:7], 0, v[20:21]
	v_mul_f32_e32 v9, v11, v11
	global_store_dwordx4 v[14:15], v[10:13], off
	v_cvt_pk_bf16_f32 v14, v10, v11
	v_fmac_f32_e32 v9, v10, v10
	v_mul_f32_e32 v10, v13, v13
	v_fmac_f32_e32 v10, v12, v12
	v_and_b32_e32 v11, 64, v210
	v_add_f32_e32 v9, v9, v10
	v_xor_b32_e32 v10, 16, v210
	v_add_u32_e32 v11, 64, v11
	v_cmp_lt_i32_e32 vcc, v10, v11
	v_cvt_pk_bf16_f32 v15, v12, v13
	v_lshl_add_u64 v[16:17], v[18:19], 1, s[8:9]
	v_cndmask_b32_e32 v10, v210, v10, vcc
	v_lshlrev_b32_e32 v10, 2, v10
	ds_bpermute_b32 v10, v10, v9
	global_store_dwordx2 v[16:17], v[14:15], off
	s_waitcnt lgkmcnt(0)
	v_add_f32_e32 v9, v9, v10
	v_xor_b32_e32 v10, 32, v210
	v_cmp_lt_i32_e32 vcc, v10, v11
	s_nop 1
	v_cndmask_b32_e32 v10, v210, v10, vcc
	v_lshlrev_b32_e32 v10, 2, v10
	ds_bpermute_b32 v10, v10, v9
	s_and_saveexec_b64 s[18:19], s[0:1]
	s_cbranch_execz .LBB0_336
	s_waitcnt lgkmcnt(0)
	v_add_f32_e32 v9, v9, v10
	global_atomic_add_f32 v[4:5], v9, off offset:256
	s_branch .LBB0_336

.LBB0_855:
	s_lshl_b32 s0, s46, 8
	s_add_i32 s0, s0, s40
	v_and_or_b32 v136, v206, 15, s0
	s_and_b64 vcc, exec, s[8:9]
	s_lshl_b32 s0, s45, 8
	v_lshrrev_b32_e32 v140, 1, v206
	v_and_or_b32 v140, v140, 24, s0
	v_or_b32_e32 v140, s41, v140
	s_mov_b64 s[0:1], -1
	s_mov_b32 s49, s59
	v_lshlrev_b32_e32 v134, 11, v136
	v_lshl_add_u32 v134, v140, 1, v134
	v_lshlrev_b32_e32 v136, 5, v136
	v_add_u32_e32 v147, 0x1000, v136
	v_add_u32_e32 v135, 0x8000, v134
	v_add_u32_e32 v137, 0x10000, v134
	v_add_u32_e32 v141, 0x18000, v134
	v_add_u32_e32 v142, 0x40000, v134
	v_add_u32_e32 v144, 0x48000, v134
	v_add_u32_e32 v145, 0x50000, v134
	v_add_u32_e32 v146, 0x58000, v134
	global_load_dwordx4 v[152:155], v136, s[12:13]
	global_load_dwordx4 v[156:159], v136, s[12:13] offset:16
	global_load_dwordx4 v[160:163], v136, s[12:13] offset:512
	global_load_dwordx4 v[164:167], v136, s[12:13] offset:528
	global_load_dwordx4 v[168:171], v136, s[12:13] offset:1024
	global_load_dwordx4 v[172:175], v136, s[12:13] offset:1040
	global_load_dwordx4 v[176:179], v136, s[12:13] offset:1536
	global_load_dwordx4 v[180:183], v136, s[12:13] offset:1552
	global_load_dwordx4 v[184:187], v147, s[12:13]
	global_load_dwordx4 v[188:191], v147, s[12:13] offset:16
	global_load_dwordx4 v[192:195], v147, s[12:13] offset:512
	global_load_dwordx4 v[196:199], v147, s[12:13] offset:528
	global_load_dwordx4 v[200:203], v147, s[12:13] offset:1024
	global_load_dwordx4 v[212:215], v147, s[12:13] offset:1040
	global_load_dwordx4 v[220:223], v147, s[12:13] offset:1536
	global_load_dwordx4 v[224:227], v147, s[12:13] offset:1552
	s_waitcnt vmcnt(14)
	v_add_f32_e32 v150, v152, v153
	v_add_f32_e32 v151, v154, v155
	v_add_f32_e32 v204, v156, v157
	v_add_f32_e32 v205, v158, v159
	v_add_f32_e32 v150, v150, v151
	v_add_f32_e32 v204, v204, v205
	v_add_f32_e32 v150, v150, v204
	v_fmamk_f32 v150, v150, 0x3b2aaaab, v207
	v_rsq_f32_e32 v150, v150
	s_nop 0
	v_pk_mul_f32 v[112:113], v[112:113], v[150:151] op_sel_hi:[1,0]
	v_pk_mul_f32 v[114:115], v[114:115], v[150:151] op_sel_hi:[1,0]
	v_pk_mul_f32 v[116:117], v[116:117], v[150:151] op_sel_hi:[1,0]
	v_pk_mul_f32 v[118:119], v[118:119], v[150:151] op_sel_hi:[1,0]
	v_cvt_pk_bf16_f32 v112, v112, v113
	v_cvt_pk_bf16_f32 v113, v114, v115
	v_cvt_pk_bf16_f32 v114, v116, v117
	v_cvt_pk_bf16_f32 v115, v118, v119
	global_store_dwordx4 v134, v[112:115], s[10:11]
	v_pk_mul_f32 v[120:121], v[120:121], v[150:151] op_sel_hi:[1,0]
	v_pk_mul_f32 v[122:123], v[122:123], v[150:151] op_sel_hi:[1,0]
	v_pk_mul_f32 v[124:125], v[124:125], v[150:151] op_sel_hi:[1,0]
	v_pk_mul_f32 v[126:127], v[126:127], v[150:151] op_sel_hi:[1,0]
	v_cvt_pk_bf16_f32 v120, v120, v121
	v_cvt_pk_bf16_f32 v121, v122, v123
	v_cvt_pk_bf16_f32 v122, v124, v125
	v_cvt_pk_bf16_f32 v123, v126, v127
	global_store_dwordx4 v134, v[120:123], s[10:11] offset:256
	s_waitcnt vmcnt(14)
	v_add_f32_e32 v150, v160, v161
	v_add_f32_e32 v151, v162, v163
	v_add_f32_e32 v204, v164, v165
	v_add_f32_e32 v205, v166, v167
	v_add_f32_e32 v150, v150, v151
	v_add_f32_e32 v204, v204, v205
	v_add_f32_e32 v150, v150, v204
	v_fmamk_f32 v150, v150, 0x3b2aaaab, v207
	v_rsq_f32_e32 v150, v150
	s_nop 0
	v_pk_mul_f32 v[96:97], v[96:97], v[150:151] op_sel_hi:[1,0]
	v_pk_mul_f32 v[98:99], v[98:99], v[150:151] op_sel_hi:[1,0]
	v_pk_mul_f32 v[100:101], v[100:101], v[150:151] op_sel_hi:[1,0]
	v_pk_mul_f32 v[102:103], v[102:103], v[150:151] op_sel_hi:[1,0]
	v_cvt_pk_bf16_f32 v96, v96, v97
	v_cvt_pk_bf16_f32 v97, v98, v99
	v_cvt_pk_bf16_f32 v98, v100, v101
	v_cvt_pk_bf16_f32 v99, v102, v103
	global_store_dwordx4 v135, v[96:99], s[10:11]
	v_pk_mul_f32 v[104:105], v[104:105], v[150:151] op_sel_hi:[1,0]
	v_pk_mul_f32 v[106:107], v[106:107], v[150:151] op_sel_hi:[1,0]
	v_pk_mul_f32 v[108:109], v[108:109], v[150:151] op_sel_hi:[1,0]
	v_pk_mul_f32 v[110:111], v[110:111], v[150:151] op_sel_hi:[1,0]
	v_cvt_pk_bf16_f32 v104, v104, v105
	v_cvt_pk_bf16_f32 v105, v106, v107
	v_cvt_pk_bf16_f32 v106, v108, v109
	v_cvt_pk_bf16_f32 v107, v110, v111
	global_store_dwordx4 v135, v[104:107], s[10:11] offset:256
	s_waitcnt vmcnt(14)
	v_add_f32_e32 v150, v168, v169
	v_add_f32_e32 v151, v170, v171
	v_add_f32_e32 v204, v172, v173
	v_add_f32_e32 v205, v174, v175
	v_add_f32_e32 v150, v150, v151
	v_add_f32_e32 v204, v204, v205
	v_add_f32_e32 v150, v150, v204
	v_fmamk_f32 v150, v150, 0x3b2aaaab, v207
	v_rsq_f32_e32 v150, v150
	s_nop 0
	v_pk_mul_f32 v[80:81], v[80:81], v[150:151] op_sel_hi:[1,0]
	v_pk_mul_f32 v[82:83], v[82:83], v[150:151] op_sel_hi:[1,0]
	v_pk_mul_f32 v[84:85], v[84:85], v[150:151] op_sel_hi:[1,0]
	v_pk_mul_f32 v[86:87], v[86:87], v[150:151] op_sel_hi:[1,0]
	v_cvt_pk_bf16_f32 v80, v80, v81
	v_cvt_pk_bf16_f32 v81, v82, v83
	v_cvt_pk_bf16_f32 v82, v84, v85
	v_cvt_pk_bf16_f32 v83, v86, v87
	global_store_dwordx4 v137, v[80:83], s[10:11]
	v_pk_mul_f32 v[88:89], v[88:89], v[150:151] op_sel_hi:[1,0]
	v_pk_mul_f32 v[90:91], v[90:91], v[150:151] op_sel_hi:[1,0]
	v_pk_mul_f32 v[92:93], v[92:93], v[150:151] op_sel_hi:[1,0]
	v_pk_mul_f32 v[94:95], v[94:95], v[150:151] op_sel_hi:[1,0]
	v_cvt_pk_bf16_f32 v88, v88, v89
	v_cvt_pk_bf16_f32 v89, v90, v91
	v_cvt_pk_bf16_f32 v90, v92, v93
	v_cvt_pk_bf16_f32 v91, v94, v95
	global_store_dwordx4 v137, v[88:91], s[10:11] offset:256
	s_waitcnt vmcnt(14)
	v_add_f32_e32 v150, v176, v177
	v_add_f32_e32 v151, v178, v179
	v_add_f32_e32 v204, v180, v181
	v_add_f32_e32 v205, v182, v183
	v_add_f32_e32 v150, v150, v151
	v_add_f32_e32 v204, v204, v205
	v_add_f32_e32 v150, v150, v204
	v_fmamk_f32 v150, v150, 0x3b2aaaab, v207
	v_rsq_f32_e32 v150, v150
	s_nop 0
	v_pk_mul_f32 v[64:65], v[64:65], v[150:151] op_sel_hi:[1,0]
	v_pk_mul_f32 v[66:67], v[66:67], v[150:151] op_sel_hi:[1,0]
	v_pk_mul_f32 v[68:69], v[68:69], v[150:151] op_sel_hi:[1,0]
	v_pk_mul_f32 v[70:71], v[70:71], v[150:151] op_sel_hi:[1,0]
	v_cvt_pk_bf16_f32 v64, v64, v65
	v_cvt_pk_bf16_f32 v65, v66, v67
	v_cvt_pk_bf16_f32 v66, v68, v69
	v_cvt_pk_bf16_f32 v67, v70, v71
	global_store_dwordx4 v141, v[64:67], s[10:11]
	v_pk_mul_f32 v[72:73], v[72:73], v[150:151] op_sel_hi:[1,0]
	v_pk_mul_f32 v[74:75], v[74:75], v[150:151] op_sel_hi:[1,0]
	v_pk_mul_f32 v[76:77], v[76:77], v[150:151] op_sel_hi:[1,0]
	v_pk_mul_f32 v[78:79], v[78:79], v[150:151] op_sel_hi:[1,0]
	v_cvt_pk_bf16_f32 v72, v72, v73
	v_cvt_pk_bf16_f32 v73, v74, v75
	v_cvt_pk_bf16_f32 v74, v76, v77
	v_cvt_pk_bf16_f32 v75, v78, v79
	global_store_dwordx4 v141, v[72:75], s[10:11] offset:256
	s_waitcnt vmcnt(14)
	v_add_f32_e32 v150, v184, v185
	v_add_f32_e32 v151, v186, v187
	v_add_f32_e32 v204, v188, v189
	v_add_f32_e32 v205, v190, v191
	v_add_f32_e32 v150, v150, v151
	v_add_f32_e32 v204, v204, v205
	v_add_f32_e32 v150, v150, v204
	v_fmamk_f32 v150, v150, 0x3b2aaaab, v207
	v_rsq_f32_e32 v150, v150
	s_nop 0
	v_pk_mul_f32 v[48:49], v[48:49], v[150:151] op_sel_hi:[1,0]
	v_pk_mul_f32 v[50:51], v[50:51], v[150:151] op_sel_hi:[1,0]
	v_pk_mul_f32 v[52:53], v[52:53], v[150:151] op_sel_hi:[1,0]
	v_pk_mul_f32 v[54:55], v[54:55], v[150:151] op_sel_hi:[1,0]
	v_cvt_pk_bf16_f32 v48, v48, v49
	v_cvt_pk_bf16_f32 v49, v50, v51
	v_cvt_pk_bf16_f32 v50, v52, v53
	v_cvt_pk_bf16_f32 v51, v54, v55
	global_store_dwordx4 v142, v[48:51], s[10:11]
	v_pk_mul_f32 v[56:57], v[56:57], v[150:151] op_sel_hi:[1,0]
	v_pk_mul_f32 v[58:59], v[58:59], v[150:151] op_sel_hi:[1,0]
	v_pk_mul_f32 v[60:61], v[60:61], v[150:151] op_sel_hi:[1,0]
	v_pk_mul_f32 v[62:63], v[62:63], v[150:151] op_sel_hi:[1,0]
	v_cvt_pk_bf16_f32 v56, v56, v57
	v_cvt_pk_bf16_f32 v57, v58, v59
	v_cvt_pk_bf16_f32 v58, v60, v61
	v_cvt_pk_bf16_f32 v59, v62, v63
	global_store_dwordx4 v142, v[56:59], s[10:11] offset:256
	s_waitcnt vmcnt(14)
	v_add_f32_e32 v150, v192, v193
	v_add_f32_e32 v151, v194, v195
	v_add_f32_e32 v204, v196, v197
	v_add_f32_e32 v205, v198, v199
	v_add_f32_e32 v150, v150, v151
	v_add_f32_e32 v204, v204, v205
	v_add_f32_e32 v150, v150, v204
	v_fmamk_f32 v150, v150, 0x3b2aaaab, v207
	v_rsq_f32_e32 v150, v150
	s_nop 0
	v_pk_mul_f32 v[32:33], v[32:33], v[150:151] op_sel_hi:[1,0]
	v_pk_mul_f32 v[34:35], v[34:35], v[150:151] op_sel_hi:[1,0]
	v_pk_mul_f32 v[36:37], v[36:37], v[150:151] op_sel_hi:[1,0]
	v_pk_mul_f32 v[38:39], v[38:39], v[150:151] op_sel_hi:[1,0]
	v_cvt_pk_bf16_f32 v32, v32, v33
	v_cvt_pk_bf16_f32 v33, v34, v35
	v_cvt_pk_bf16_f32 v34, v36, v37
	v_cvt_pk_bf16_f32 v35, v38, v39
	global_store_dwordx4 v144, v[32:35], s[10:11]
	v_pk_mul_f32 v[40:41], v[40:41], v[150:151] op_sel_hi:[1,0]
	v_pk_mul_f32 v[42:43], v[42:43], v[150:151] op_sel_hi:[1,0]
	v_pk_mul_f32 v[44:45], v[44:45], v[150:151] op_sel_hi:[1,0]
	v_pk_mul_f32 v[46:47], v[46:47], v[150:151] op_sel_hi:[1,0]
	v_cvt_pk_bf16_f32 v40, v40, v41
	v_cvt_pk_bf16_f32 v41, v42, v43
	v_cvt_pk_bf16_f32 v42, v44, v45
	v_cvt_pk_bf16_f32 v43, v46, v47
	global_store_dwordx4 v144, v[40:43], s[10:11] offset:256
	s_waitcnt vmcnt(14)
	v_add_f32_e32 v150, v200, v201
	v_add_f32_e32 v151, v202, v203
	v_add_f32_e32 v204, v212, v213
	v_add_f32_e32 v205, v214, v215
	v_add_f32_e32 v150, v150, v151
	v_add_f32_e32 v204, v204, v205
	v_add_f32_e32 v150, v150, v204
	v_fmamk_f32 v150, v150, 0x3b2aaaab, v207
	v_rsq_f32_e32 v150, v150
	s_nop 0
	v_pk_mul_f32 v[16:17], v[16:17], v[150:151] op_sel_hi:[1,0]
	v_pk_mul_f32 v[18:19], v[18:19], v[150:151] op_sel_hi:[1,0]
	v_pk_mul_f32 v[20:21], v[20:21], v[150:151] op_sel_hi:[1,0]
	v_pk_mul_f32 v[22:23], v[22:23], v[150:151] op_sel_hi:[1,0]
	v_cvt_pk_bf16_f32 v16, v16, v17
	v_cvt_pk_bf16_f32 v17, v18, v19
	v_cvt_pk_bf16_f32 v18, v20, v21
	v_cvt_pk_bf16_f32 v19, v22, v23
	global_store_dwordx4 v145, v[16:19], s[10:11]
	v_pk_mul_f32 v[24:25], v[24:25], v[150:151] op_sel_hi:[1,0]
	v_pk_mul_f32 v[26:27], v[26:27], v[150:151] op_sel_hi:[1,0]
	v_pk_mul_f32 v[28:29], v[28:29], v[150:151] op_sel_hi:[1,0]
	v_pk_mul_f32 v[30:31], v[30:31], v[150:151] op_sel_hi:[1,0]
	v_cvt_pk_bf16_f32 v24, v24, v25
	v_cvt_pk_bf16_f32 v25, v26, v27
	v_cvt_pk_bf16_f32 v26, v28, v29
	v_cvt_pk_bf16_f32 v27, v30, v31
	global_store_dwordx4 v145, v[24:27], s[10:11] offset:256
	s_waitcnt vmcnt(14)
	v_add_f32_e32 v150, v220, v221
	v_add_f32_e32 v151, v222, v223
	v_add_f32_e32 v204, v224, v225
	v_add_f32_e32 v205, v226, v227
	v_add_f32_e32 v150, v150, v151
	v_add_f32_e32 v204, v204, v205
	v_add_f32_e32 v150, v150, v204
	v_fmamk_f32 v150, v150, 0x3b2aaaab, v207
	v_rsq_f32_e32 v150, v150
	s_nop 0
	v_pk_mul_f32 v[0:1], v[0:1], v[150:151] op_sel_hi:[1,0]
	v_pk_mul_f32 v[2:3], v[2:3], v[150:151] op_sel_hi:[1,0]
	v_pk_mul_f32 v[4:5], v[4:5], v[150:151] op_sel_hi:[1,0]
	v_pk_mul_f32 v[6:7], v[6:7], v[150:151] op_sel_hi:[1,0]
	v_cvt_pk_bf16_f32 v0, v0, v1
	v_cvt_pk_bf16_f32 v1, v2, v3
	v_cvt_pk_bf16_f32 v2, v4, v5
	v_cvt_pk_bf16_f32 v3, v6, v7
	global_store_dwordx4 v146, v[0:3], s[10:11]
	v_pk_mul_f32 v[8:9], v[8:9], v[150:151] op_sel_hi:[1,0]
	v_pk_mul_f32 v[10:11], v[10:11], v[150:151] op_sel_hi:[1,0]
	v_pk_mul_f32 v[12:13], v[12:13], v[150:151] op_sel_hi:[1,0]
	v_pk_mul_f32 v[14:15], v[14:15], v[150:151] op_sel_hi:[1,0]
	v_cvt_pk_bf16_f32 v8, v8, v9
	v_cvt_pk_bf16_f32 v9, v10, v11
	v_cvt_pk_bf16_f32 v10, v12, v13
	v_cvt_pk_bf16_f32 v11, v14, v15
	global_store_dwordx4 v146, v[8:11], s[10:11] offset:256
	s_cbranch_vccnz .LBB0_844
	s_andn2_b64 vcc, exec, s[4:5]
	s_cbranch_vccnz .LBB0_843
	s_barrier
	s_branch .LBB0_843

.LBB0_873:
	s_lshl_b32 s17, s49, 8
	s_add_i32 s17, s17, s44
	v_and_or_b32 v136, v206, 15, s17
	s_mov_b64 s[24:25], -1
	s_lshl_b32 s17, s48, 8
	v_lshrrev_b32_e32 v140, 1, v206
	v_and_or_b32 v140, v140, 24, s17
	v_or_b32_e32 v140, s45, v140
	s_andn2_b64 vcc, exec, s[0:1]
	v_lshlrev_b32_e32 v134, 10, v136
	v_lshl_add_u32 v134, v140, 1, v134
	v_lshlrev_b32_e32 v136, 4, v136
	v_add_u32_e32 v135, 0x4000, v134
	v_add_u32_e32 v137, 0x8000, v134
	v_add_u32_e32 v141, 0xc000, v134
	v_add_u32_e32 v142, 0x20000, v134
	v_add_u32_e32 v144, 0x24000, v134
	v_add_u32_e32 v145, 0x28000, v134
	v_add_u32_e32 v146, 0x2c000, v134
	global_load_dwordx4 v[152:155], v136, s[4:5]
	global_load_dwordx4 v[156:159], v136, s[4:5] offset:256
	global_load_dwordx4 v[160:163], v136, s[4:5] offset:512
	global_load_dwordx4 v[164:167], v136, s[4:5] offset:768
	global_load_dwordx4 v[168:171], v136, s[4:5] offset:2048
	global_load_dwordx4 v[172:175], v136, s[4:5] offset:2304
	global_load_dwordx4 v[176:179], v136, s[4:5] offset:2560
	global_load_dwordx4 v[180:183], v136, s[4:5] offset:2816
	s_waitcnt vmcnt(7)
	v_add_f32_e32 v150, v153, v152
	v_add_f32_e32 v151, v154, v155
	v_add_f32_e32 v150, v150, v151
	v_fmamk_f32 v150, v150, 0x3b800000, v207
	v_rsq_f32_e32 v150, v150
	s_nop 0
	v_pk_mul_f32 v[112:113], v[112:113], v[150:151] op_sel_hi:[1,0]
	v_pk_mul_f32 v[114:115], v[114:115], v[150:151] op_sel_hi:[1,0]
	v_pk_mul_f32 v[116:117], v[116:117], v[150:151] op_sel_hi:[1,0]
	v_pk_mul_f32 v[118:119], v[118:119], v[150:151] op_sel_hi:[1,0]
	v_cvt_pk_bf16_f32 v112, v112, v113
	v_cvt_pk_bf16_f32 v113, v114, v115
	v_cvt_pk_bf16_f32 v114, v116, v117
	v_cvt_pk_bf16_f32 v115, v118, v119
	global_store_dwordx4 v134, v[112:115], s[10:11]
	v_pk_mul_f32 v[120:121], v[120:121], v[150:151] op_sel_hi:[1,0]
	v_pk_mul_f32 v[122:123], v[122:123], v[150:151] op_sel_hi:[1,0]
	v_pk_mul_f32 v[124:125], v[124:125], v[150:151] op_sel_hi:[1,0]
	v_pk_mul_f32 v[126:127], v[126:127], v[150:151] op_sel_hi:[1,0]
	v_cvt_pk_bf16_f32 v120, v120, v121
	v_cvt_pk_bf16_f32 v121, v122, v123
	v_cvt_pk_bf16_f32 v122, v124, v125
	v_cvt_pk_bf16_f32 v123, v126, v127
	global_store_dwordx4 v134, v[120:123], s[10:11] offset:256
	s_waitcnt vmcnt(8)
	v_add_f32_e32 v150, v157, v156
	v_add_f32_e32 v151, v158, v159
	v_add_f32_e32 v150, v150, v151
	v_fmamk_f32 v150, v150, 0x3b800000, v207
	v_rsq_f32_e32 v150, v150
	s_nop 0
	v_pk_mul_f32 v[96:97], v[96:97], v[150:151] op_sel_hi:[1,0]
	v_pk_mul_f32 v[98:99], v[98:99], v[150:151] op_sel_hi:[1,0]
	v_pk_mul_f32 v[100:101], v[100:101], v[150:151] op_sel_hi:[1,0]
	v_pk_mul_f32 v[102:103], v[102:103], v[150:151] op_sel_hi:[1,0]
	v_cvt_pk_bf16_f32 v96, v96, v97
	v_cvt_pk_bf16_f32 v97, v98, v99
	v_cvt_pk_bf16_f32 v98, v100, v101
	v_cvt_pk_bf16_f32 v99, v102, v103
	global_store_dwordx4 v135, v[96:99], s[10:11]
	v_pk_mul_f32 v[104:105], v[104:105], v[150:151] op_sel_hi:[1,0]
	v_pk_mul_f32 v[106:107], v[106:107], v[150:151] op_sel_hi:[1,0]
	v_pk_mul_f32 v[108:109], v[108:109], v[150:151] op_sel_hi:[1,0]
	v_pk_mul_f32 v[110:111], v[110:111], v[150:151] op_sel_hi:[1,0]
	v_cvt_pk_bf16_f32 v104, v104, v105
	v_cvt_pk_bf16_f32 v105, v106, v107
	v_cvt_pk_bf16_f32 v106, v108, v109
	v_cvt_pk_bf16_f32 v107, v110, v111
	global_store_dwordx4 v135, v[104:107], s[10:11] offset:256
	s_waitcnt vmcnt(9)
	v_add_f32_e32 v150, v161, v160
	v_add_f32_e32 v151, v162, v163
	v_add_f32_e32 v150, v150, v151
	v_fmamk_f32 v150, v150, 0x3b800000, v207
	v_rsq_f32_e32 v150, v150
	s_nop 0
	v_pk_mul_f32 v[80:81], v[80:81], v[150:151] op_sel_hi:[1,0]
	v_pk_mul_f32 v[82:83], v[82:83], v[150:151] op_sel_hi:[1,0]
	v_pk_mul_f32 v[84:85], v[84:85], v[150:151] op_sel_hi:[1,0]
	v_pk_mul_f32 v[86:87], v[86:87], v[150:151] op_sel_hi:[1,0]
	v_cvt_pk_bf16_f32 v80, v80, v81
	v_cvt_pk_bf16_f32 v81, v82, v83
	v_cvt_pk_bf16_f32 v82, v84, v85
	v_cvt_pk_bf16_f32 v83, v86, v87
	global_store_dwordx4 v137, v[80:83], s[10:11]
	v_pk_mul_f32 v[88:89], v[88:89], v[150:151] op_sel_hi:[1,0]
	v_pk_mul_f32 v[90:91], v[90:91], v[150:151] op_sel_hi:[1,0]
	v_pk_mul_f32 v[92:93], v[92:93], v[150:151] op_sel_hi:[1,0]
	v_pk_mul_f32 v[94:95], v[94:95], v[150:151] op_sel_hi:[1,0]
	v_cvt_pk_bf16_f32 v88, v88, v89
	v_cvt_pk_bf16_f32 v89, v90, v91
	v_cvt_pk_bf16_f32 v90, v92, v93
	v_cvt_pk_bf16_f32 v91, v94, v95
	global_store_dwordx4 v137, v[88:91], s[10:11] offset:256
	s_waitcnt vmcnt(10)
	v_add_f32_e32 v150, v165, v164
	v_add_f32_e32 v151, v166, v167
	v_add_f32_e32 v150, v150, v151
	v_fmamk_f32 v150, v150, 0x3b800000, v207
	v_rsq_f32_e32 v150, v150
	s_nop 0
	v_pk_mul_f32 v[64:65], v[64:65], v[150:151] op_sel_hi:[1,0]
	v_pk_mul_f32 v[66:67], v[66:67], v[150:151] op_sel_hi:[1,0]
	v_pk_mul_f32 v[68:69], v[68:69], v[150:151] op_sel_hi:[1,0]
	v_pk_mul_f32 v[70:71], v[70:71], v[150:151] op_sel_hi:[1,0]
	v_cvt_pk_bf16_f32 v64, v64, v65
	v_cvt_pk_bf16_f32 v65, v66, v67
	v_cvt_pk_bf16_f32 v66, v68, v69
	v_cvt_pk_bf16_f32 v67, v70, v71
	global_store_dwordx4 v141, v[64:67], s[10:11]
	v_pk_mul_f32 v[72:73], v[72:73], v[150:151] op_sel_hi:[1,0]
	v_pk_mul_f32 v[74:75], v[74:75], v[150:151] op_sel_hi:[1,0]
	v_pk_mul_f32 v[76:77], v[76:77], v[150:151] op_sel_hi:[1,0]
	v_pk_mul_f32 v[78:79], v[78:79], v[150:151] op_sel_hi:[1,0]
	v_cvt_pk_bf16_f32 v72, v72, v73
	v_cvt_pk_bf16_f32 v73, v74, v75
	v_cvt_pk_bf16_f32 v74, v76, v77
	v_cvt_pk_bf16_f32 v75, v78, v79
	global_store_dwordx4 v141, v[72:75], s[10:11] offset:256
	s_waitcnt vmcnt(11)
	v_add_f32_e32 v150, v169, v168
	v_add_f32_e32 v151, v170, v171
	v_add_f32_e32 v150, v150, v151
	v_fmamk_f32 v150, v150, 0x3b800000, v207
	v_rsq_f32_e32 v150, v150
	s_nop 0
	v_pk_mul_f32 v[48:49], v[48:49], v[150:151] op_sel_hi:[1,0]
	v_pk_mul_f32 v[50:51], v[50:51], v[150:151] op_sel_hi:[1,0]
	v_pk_mul_f32 v[52:53], v[52:53], v[150:151] op_sel_hi:[1,0]
	v_pk_mul_f32 v[54:55], v[54:55], v[150:151] op_sel_hi:[1,0]
	v_cvt_pk_bf16_f32 v48, v48, v49
	v_cvt_pk_bf16_f32 v49, v50, v51
	v_cvt_pk_bf16_f32 v50, v52, v53
	v_cvt_pk_bf16_f32 v51, v54, v55
	global_store_dwordx4 v142, v[48:51], s[10:11]
	v_pk_mul_f32 v[56:57], v[56:57], v[150:151] op_sel_hi:[1,0]
	v_pk_mul_f32 v[58:59], v[58:59], v[150:151] op_sel_hi:[1,0]
	v_pk_mul_f32 v[60:61], v[60:61], v[150:151] op_sel_hi:[1,0]
	v_pk_mul_f32 v[62:63], v[62:63], v[150:151] op_sel_hi:[1,0]
	v_cvt_pk_bf16_f32 v56, v56, v57
	v_cvt_pk_bf16_f32 v57, v58, v59
	v_cvt_pk_bf16_f32 v58, v60, v61
	v_cvt_pk_bf16_f32 v59, v62, v63
	global_store_dwordx4 v142, v[56:59], s[10:11] offset:256
	s_waitcnt vmcnt(12)
	v_add_f32_e32 v150, v173, v172
	v_add_f32_e32 v151, v174, v175
	v_add_f32_e32 v150, v150, v151
	v_fmamk_f32 v150, v150, 0x3b800000, v207
	v_rsq_f32_e32 v150, v150
	s_nop 0
	v_pk_mul_f32 v[32:33], v[32:33], v[150:151] op_sel_hi:[1,0]
	v_pk_mul_f32 v[34:35], v[34:35], v[150:151] op_sel_hi:[1,0]
	v_pk_mul_f32 v[36:37], v[36:37], v[150:151] op_sel_hi:[1,0]
	v_pk_mul_f32 v[38:39], v[38:39], v[150:151] op_sel_hi:[1,0]
	v_cvt_pk_bf16_f32 v32, v32, v33
	v_cvt_pk_bf16_f32 v33, v34, v35
	v_cvt_pk_bf16_f32 v34, v36, v37
	v_cvt_pk_bf16_f32 v35, v38, v39
	global_store_dwordx4 v144, v[32:35], s[10:11]
	v_pk_mul_f32 v[40:41], v[40:41], v[150:151] op_sel_hi:[1,0]
	v_pk_mul_f32 v[42:43], v[42:43], v[150:151] op_sel_hi:[1,0]
	v_pk_mul_f32 v[44:45], v[44:45], v[150:151] op_sel_hi:[1,0]
	v_pk_mul_f32 v[46:47], v[46:47], v[150:151] op_sel_hi:[1,0]
	v_cvt_pk_bf16_f32 v40, v40, v41
	v_cvt_pk_bf16_f32 v41, v42, v43
	v_cvt_pk_bf16_f32 v42, v44, v45
	v_cvt_pk_bf16_f32 v43, v46, v47
	global_store_dwordx4 v144, v[40:43], s[10:11] offset:256
	s_waitcnt vmcnt(13)
	v_add_f32_e32 v150, v177, v176
	v_add_f32_e32 v151, v178, v179
	v_add_f32_e32 v150, v150, v151
	v_fmamk_f32 v150, v150, 0x3b800000, v207
	v_rsq_f32_e32 v150, v150
	s_nop 0
	v_pk_mul_f32 v[16:17], v[16:17], v[150:151] op_sel_hi:[1,0]
	v_pk_mul_f32 v[18:19], v[18:19], v[150:151] op_sel_hi:[1,0]
	v_pk_mul_f32 v[20:21], v[20:21], v[150:151] op_sel_hi:[1,0]
	v_pk_mul_f32 v[22:23], v[22:23], v[150:151] op_sel_hi:[1,0]
	v_cvt_pk_bf16_f32 v16, v16, v17
	v_cvt_pk_bf16_f32 v17, v18, v19
	v_cvt_pk_bf16_f32 v18, v20, v21
	v_cvt_pk_bf16_f32 v19, v22, v23
	global_store_dwordx4 v145, v[16:19], s[10:11]
	v_pk_mul_f32 v[24:25], v[24:25], v[150:151] op_sel_hi:[1,0]
	v_pk_mul_f32 v[26:27], v[26:27], v[150:151] op_sel_hi:[1,0]
	v_pk_mul_f32 v[28:29], v[28:29], v[150:151] op_sel_hi:[1,0]
	v_pk_mul_f32 v[30:31], v[30:31], v[150:151] op_sel_hi:[1,0]
	v_cvt_pk_bf16_f32 v24, v24, v25
	v_cvt_pk_bf16_f32 v25, v26, v27
	v_cvt_pk_bf16_f32 v26, v28, v29
	v_cvt_pk_bf16_f32 v27, v30, v31
	global_store_dwordx4 v145, v[24:27], s[10:11] offset:256
	s_waitcnt vmcnt(14)
	v_add_f32_e32 v150, v181, v180
	v_add_f32_e32 v151, v182, v183
	v_add_f32_e32 v150, v150, v151
	v_fmamk_f32 v150, v150, 0x3b800000, v207
	v_rsq_f32_e32 v150, v150
	s_nop 0
	v_pk_mul_f32 v[0:1], v[0:1], v[150:151] op_sel_hi:[1,0]
	v_pk_mul_f32 v[2:3], v[2:3], v[150:151] op_sel_hi:[1,0]
	v_pk_mul_f32 v[4:5], v[4:5], v[150:151] op_sel_hi:[1,0]
	v_pk_mul_f32 v[6:7], v[6:7], v[150:151] op_sel_hi:[1,0]
	v_cvt_pk_bf16_f32 v0, v0, v1
	v_cvt_pk_bf16_f32 v1, v2, v3
	v_cvt_pk_bf16_f32 v2, v4, v5
	v_cvt_pk_bf16_f32 v3, v6, v7
	global_store_dwordx4 v146, v[0:3], s[10:11]
	v_pk_mul_f32 v[8:9], v[8:9], v[150:151] op_sel_hi:[1,0]
	v_pk_mul_f32 v[10:11], v[10:11], v[150:151] op_sel_hi:[1,0]
	v_pk_mul_f32 v[12:13], v[12:13], v[150:151] op_sel_hi:[1,0]
	v_pk_mul_f32 v[14:15], v[14:15], v[150:151] op_sel_hi:[1,0]
	v_cvt_pk_bf16_f32 v8, v8, v9
	v_cvt_pk_bf16_f32 v9, v10, v11
	v_cvt_pk_bf16_f32 v10, v12, v13
	v_cvt_pk_bf16_f32 v11, v14, v15
	global_store_dwordx4 v146, v[8:11], s[10:11] offset:256
	s_cbranch_vccnz .LBB0_864
	s_andn2_b64 vcc, exec, s[8:9]
	s_cbranch_vccnz .LBB0_863
	s_barrier
	s_branch .LBB0_863

.LBB0_947:
	s_or_b64 exec, exec, s[0:1]
	v_mov_b32_e32 v32, v206
	s_mov_b32 s2, s49
	s_waitcnt lgkmcnt(0)
	s_barrier
	s_add_u32 s4, s86, s2
	v_readfirstlane_b32 s0, v32
	s_addc_u32 s5, s87, 0
	s_ashr_i32 s14, s0, 6
	s_add_i32 s20, s14, s97
	v_and_b32_e32 v33, 7, v32
	v_bfe_u32 v30, v32, 3, 3
	s_cmpk_gt_i32 s20, 0x7fff
	v_lshlrev_b32_e32 v31, 1, v33
	s_cbranch_scc1 .LBB0_950
	v_cvt_f32_ubyte0_e32 v0, v31
	v_mul_f32_e32 v1, 0xbf549a78, v0
	s_mov_b32 s0, 0xc2fc0000
	v_cmp_gt_f32_e32 vcc, s0, v1
	v_mov_b32_e32 v3, 0x42800000
	s_mov_b32 s3, s49
	v_cndmask_b32_e32 v1, 0, v3, vcc
	v_fmac_f32_e32 v1, 0xbf549a78, v0
	v_exp_f32_e32 v0, v1
	v_or_b32_e32 v1, 1, v31
	v_cvt_f32_ubyte0_e32 v1, v1
	v_mul_f32_e32 v2, 0xbf549a78, v1
	v_cmp_gt_f32_e64 s[0:1], s0, v2
	s_mov_b32 s7, s49
	v_readlane_b32 s36, v252, 21
	v_cndmask_b32_e64 v2, 0, v3, s[0:1]
	v_fmac_f32_e32 v2, 0xbf549a78, v1
	v_exp_f32_e32 v1, v2
	v_not_b32_e32 v3, 63
	v_cndmask_b32_e32 v2, 0, v3, vcc
	v_ldexp_f32 v34, v0, v2
	v_cndmask_b32_e64 v0, 0, v3, s[0:1]
	v_lshlrev_b32_e32 v148, 3, v33
	s_add_u32 s0, s4, 0xf600000
	v_lshrrev_b32_e32 v2, 2, v33
	v_lshlrev_b32_e32 v8, 5, v33
	v_mov_b32_e32 v9, v149
	v_readlane_b32 s48, v252, 33
	v_readlane_b32 s49, v252, 34
	v_ldexp_f32 v35, v1, v0
	v_and_b32_e32 v1, 64, v210
	s_addc_u32 s1, s5, 0
	v_or_b32_e32 v39, 8, v2
	v_or_b32_e32 v40, 10, v2
	v_lshl_add_u64 v[2:3], s[48:49], 0, v[8:9]
	v_lshl_add_u64 v[4:5], s[48:49], 0, v[148:149]
	s_mov_b32 s49, s7
	s_ashr_i32 s7, s14, 31
	v_xor_b32_e32 v0, 1, v210
	v_add_u32_e32 v1, 64, v1
	s_add_u32 s6, s97, s14
	v_readlane_b32 s8, v253, 44
	v_cmp_lt_i32_e32 vcc, v0, v1
	s_addc_u32 s7, s8, s7
	v_readlane_b32 s50, v252, 35
	v_cndmask_b32_e32 v0, v210, v0, vcc
	v_readlane_b32 s51, v252, 36
	s_lshl_b64 s[8:9], s[6:7], 11
	v_and_b32_e32 v10, 56, v32
	v_lshlrev_b32_e32 v36, 2, v0
	v_xor_b32_e32 v0, 2, v210
	v_lshl_add_u64 v[6:7], s[50:51], 0, v[148:149]
	v_lshl_or_b32 v14, v10, 5, s8
	v_lshlrev_b32_e32 v148, 2, v33
	v_cmp_lt_i32_e32 vcc, v0, v1
	v_or_b32_e32 v12, v14, v148
	v_mov_b32_e32 v13, s9
	v_lshlrev_b32_e32 v17, 4, v33
	v_readlane_b32 s8, v253, 47
	v_cndmask_b32_e32 v0, v210, v0, vcc
	v_lshl_add_u64 v[10:11], s[86:87], 0, v[12:13]
	v_or_b32_e32 v12, v14, v17
	v_readlane_b32 s9, v253, 48
	s_lshl_b64 s[6:7], s[6:7], 10
	v_lshlrev_b32_e32 v37, 2, v0
	v_xor_b32_e32 v0, 4, v210
	v_lshlrev_b32_e32 v16, 7, v30
	v_lshl_add_u64 v[12:13], s[8:9], 0, v[12:13]
	s_add_u32 s8, s86, s6
	v_cmp_lt_i32_e32 vcc, v0, v1
	s_addc_u32 s9, s87, s7
	v_or3_b32 v16, s6, v16, v17
	v_mov_b32_e32 v17, s7
	v_readlane_b32 s6, v253, 51
	v_cndmask_b32_e32 v0, v210, v0, vcc
	v_readlane_b32 s7, v253, 52
	v_lshlrev_b32_e32 v38, 2, v0
	v_lshlrev_b32_e32 v0, 2, v32
	s_mov_b32 s18, 0x6dc9c883
	v_readlane_b32 s16, v253, 49
	v_readlane_b32 s12, v253, 45
	v_lshl_add_u64 v[16:17], s[6:7], 0, v[16:17]
	s_lshl_b32 s6, s14, 1
	v_readlane_b32 s7, v253, 23
	v_and_b32_e32 v0, 12, v0
	v_mov_b32_e32 v1, v149
	s_mov_b32 s19, 0x3fc45f30
	v_readlane_b32 s17, v253, 50
	v_readlane_b32 s13, v253, 46
	v_readlane_b32 s36, v254, 30
	v_readlane_b32 s31, v254, 29
	v_lshl_add_u64 v[8:9], s[50:51], 0, v[8:9]
	v_lshl_add_u64 v[14:15], s[8:9], 0, v[148:149]
	s_add_i32 s6, s7, s6
	s_mov_b32 s7, s20
	v_readlane_b32 s37, v252, 22
	v_readlane_b32 s38, v252, 23
	v_readlane_b32 s39, v252, 24
	v_readlane_b32 s40, v252, 25
	v_readlane_b32 s41, v252, 26
	v_readlane_b32 s42, v252, 27
	v_readlane_b32 s43, v252, 28
	v_readlane_b32 s44, v252, 29
	v_readlane_b32 s45, v252, 30
	v_readlane_b32 s46, v252, 31
	v_readlane_b32 s47, v252, 32
	s_mov_b32 s22, 0x1b600000
	s_mov_b32 s23, 0
	s_mov_b32 s24, 0x12600000
	s_mov_b32 s25, 0
	global_load_dwordx4 v[80:83], v[2:3], off
	global_load_dwordx4 v[84:87], v[2:3], off offset:16
	global_load_dwordx2 v[88:89], v[4:5], off offset:256
	global_load_dwordx2 v[90:91], v[4:5], off offset:320
	global_load_dwordx2 v[92:93], v[6:7], off offset:256
	global_load_dwordx2 v[94:95], v[6:7], off offset:320
	global_load_dwordx4 v[96:99], v[8:9], off
	global_load_dwordx4 v[100:103], v[8:9], off offset:16
	v_lshl_add_u64 v[122:123], v[12:13], 0, s[2:3]
	global_load_dwordx4 v[104:107], v[122:123], off
	v_lshl_add_u64 v[124:125], v[10:11], 0, s[2:3]
	v_lshl_add_u64 v[124:125], v[124:125], 0, s[22:23]
	global_load_dword v108, v[124:125], off offset:128
	global_load_dword v109, v[124:125], off offset:160
	v_lshl_add_u64 v[122:123], v[14:15], 0, s[2:3]
	v_lshl_add_u64 v[122:123], v[122:123], 0, s[24:25]
	global_load_dword v110, v[122:123], off offset:800
	global_load_dword v111, v[122:123], off offset:768
	v_lshl_add_u64 v[124:125], v[16:17], 0, s[2:3]
	global_load_dwordx4 v[112:115], v[124:125], off
	s_waitcnt vmcnt(0)
.LBB0_949:
	s_and_b32 s8, s7, 0xfff
	s_add_i32 s8, s8, 16
	v_cvt_f32_u32_e32 v22, s8
	s_and_b32 s8, s7, 51
	s_and_b32 s9, s6, 8
	s_or_b32 s8, s9, s8
	v_mul_f32_e32 v18, v34, v22
	v_cvt_f64_f32_e32 v[18:19], v18
	v_mul_f64 v[20:21], v[18:19], s[18:19]
	v_rndne_f64_e32 v[20:21], v[20:21]
	v_fma_f64 v[18:19], v[18:19], s[18:19], -v[20:21]
	v_cvt_f32_f64_e32 v19, v[18:19]
	v_cos_f32_e32 v18, v19
	v_sin_f32_e32 v20, v19
	v_mul_f32_e32 v19, v35, v22
	v_cvt_f64_f32_e32 v[22:23], v19
	s_lshr_b32 s9, s7, 1
	v_mul_f64 v[24:25], v[22:23], s[18:19]
	s_and_b32 s9, s9, 4
	v_rndne_f64_e32 v[24:25], v[24:25]
	s_or_b32 s10, s8, s9
	s_ashr_i32 s8, s7, 9
	v_fma_f64 v[22:23], v[22:23], s[18:19], -v[24:25]
	s_and_b32 s8, s8, 0x3fffff8
	v_cvt_f32_f64_e32 v21, v[22:23]
	v_or_b32_e32 v22, s8, v30
	s_bfe_u32 s8, s7, 0x60006
	v_lshl_or_b32 v24, v22, 6, s8
	v_mov_b64_e32 v[22:23], s[0:1]
	s_lshr_b32 s11, s10, 2
	v_mad_i64_i32 v[22:23], s[8:9], v24, s33, v[22:23]
	s_mul_i32 s48, s10, 0xc0
	v_lshl_add_u64 v[46:47], v[10:11], 0, s[2:3]
	v_lshl_add_u64 v[26:27], v[22:23], 0, s[48:49]
	v_bitop3_b32 v22, s11, v33, 3 bitop3:0x6c
	s_mov_b32 s8, 0x1b600000
	v_lshlrev_b32_e32 v148, 4, v22
	v_bitop3_b32 v24, s11, v39, 3 bitop3:0x6c
	v_add_co_u32_e32 v54, vcc, s8, v46
	v_lshl_add_u64 v[28:29], v[12:13], 0, s[2:3]
	v_lshl_add_u64 v[22:23], v[26:27], 0, v[148:149]
	v_lshlrev_b32_e32 v148, 4, v24
	v_bitop3_b32 v41, s11, v40, 3 bitop3:0x6c
	v_addc_co_u32_e32 v55, vcc, 0, v47, vcc
	v_lshl_add_u64 v[24:25], v[26:27], 0, v[148:149]
	v_lshlrev_b32_e32 v148, 4, v41
	s_waitcnt vmcnt(6)
	v_mov_b32_e32 v42, v104
	v_mov_b32_e32 v43, v105
	v_mov_b32_e32 v44, v106
	v_mov_b32_e32 v45, v107
	v_mov_b32_e32 v41, v108
	v_mov_b32_e32 v46, v109
	v_cos_f32_e32 v19, v21
	v_sin_f32_e32 v21, v21
	s_mov_b32 s8, 0x12600000
	v_lshl_add_u64 v[24:25], v[24:25], 0, v[0:1]
	v_lshl_add_u64 v[26:27], v[26:27], 0, v[148:149]
	s_add_i32 s7, s7, s84
	s_add_i32 s6, s6, s36
	v_lshl_add_u64 v[26:27], v[26:27], 0, v[0:1]
	v_lshl_add_u64 v[10:11], v[10:11], 0, s[12:13]
	v_lshl_add_u64 v[12:13], v[12:13], 0, s[12:13]
	s_cmpk_gt_i32 s7, 0x7fff
	s_cbranch_scc1 .Lrope_nopf_q
	v_lshl_add_u64 v[122:123], v[12:13], 0, s[2:3]
	global_load_dwordx4 v[104:107], v[122:123], off
	v_lshl_add_u64 v[124:125], v[10:11], 0, s[2:3]
	v_lshl_add_u64 v[124:125], v[124:125], 0, s[22:23]
	global_load_dword v108, v[124:125], off offset:128
	global_load_dword v109, v[124:125], off offset:160
.Lrope_nopf_q:
	v_lshlrev_b32_e32 v64, 16, v42
	v_lshlrev_b32_e32 v58, 16, v46
	v_and_b32_e32 v59, 0xffff0000, v46
	v_lshlrev_b32_e32 v56, 16, v41
	v_and_b32_e32 v57, 0xffff0000, v41
	v_pk_mul_f32 v[76:77], v[56:57], v[56:57]
	v_pk_mul_f32 v[78:79], v[58:59], v[58:59]
	v_and_b32_e32 v65, 0xffff0000, v42
	v_add_f32_e32 v41, v78, v79
	v_add_f32_e32 v76, v76, v77
	v_lshlrev_b32_e32 v60, 16, v43
	v_and_b32_e32 v61, 0xffff0000, v43
	v_pk_mul_f32 v[42:43], v[64:65], v[64:65]
	v_add_f32_e32 v41, v76, v41
	v_add_f32_e32 v41, v41, v42
	v_pk_mul_f32 v[62:63], v[60:61], v[60:61]
	v_add_f32_e32 v41, v41, v43
	v_lshlrev_b32_e32 v70, 16, v44
	v_and_b32_e32 v71, 0xffff0000, v44
	v_add_f32_e32 v41, v41, v62
	v_lshlrev_b32_e32 v66, 16, v45
	v_and_b32_e32 v67, 0xffff0000, v45
	v_pk_mul_f32 v[44:45], v[70:71], v[70:71]
	v_add_f32_e32 v41, v41, v63
	v_add_f32_e32 v41, v41, v44
	v_pk_mul_f32 v[68:69], v[66:67], v[66:67]
	v_add_f32_e32 v41, v41, v45
	v_add_f32_e32 v41, v41, v68
	v_add_f32_e32 v41, v41, v69
	ds_bpermute_b32 v42, v36, v41
	s_waitcnt lgkmcnt(0)
	v_add_f32_e32 v41, v41, v42
	ds_bpermute_b32 v42, v37, v41
	s_waitcnt lgkmcnt(0)
	v_add_f32_e32 v41, v41, v42
	ds_bpermute_b32 v42, v38, v41
	s_waitcnt lgkmcnt(0)
	v_add_f32_e32 v41, v41, v42
	v_fmamk_f32 v41, v41, 0x3c2aaaab, v207
	v_rsq_f32_e32 v41, v41
	s_nop 0
	v_mul_f32_e32 v42, 0x3e16c740, v41
	v_pk_mul_f32 v[44:45], v[42:43], v[70:71] op_sel_hi:[0,1]
	v_pk_mul_f32 v[44:45], v[84:85], v[44:45]
	v_pk_mul_f32 v[50:51], v[42:43], v[66:67] op_sel_hi:[0,1]
	v_pk_mul_f32 v[50:51], v[86:87], v[50:51]
	v_pk_mul_f32 v[52:53], v[42:43], v[64:65] op_sel_hi:[0,1]
	v_pk_mul_f32 v[46:47], v[80:81], v[52:53]
	v_pk_mul_f32 v[52:53], v[42:43], v[60:61] op_sel_hi:[0,1]
	v_pk_mul_f32 v[48:49], v[82:83], v[52:53]
	v_pk_mul_f32 v[52:53], v[88:89], v[42:43] op_sel_hi:[1,0]
	v_pk_mul_f32 v[42:43], v[90:91], v[42:43] op_sel_hi:[1,0]
	v_pk_mul_f32 v[52:53], v[52:53], v[56:57]
	v_pk_mul_f32 v[42:43], v[42:43], v[58:59]
	v_cvt_pk_bf16_f32 v44, v44, v45
	v_pk_mul_f32 v[56:57], v[18:19], v[42:43]
	v_pk_mul_f32 v[42:43], v[20:21], v[42:43]
	v_pk_fma_f32 v[56:57], v[20:21], v[52:53], v[56:57]
	v_pk_fma_f32 v[52:53], v[18:19], v[52:53], v[42:43] neg_lo:[0,0,1] neg_hi:[0,0,1]
	v_cvt_pk_bf16_f32 v42, v46, v47
	v_cvt_pk_bf16_f32 v43, v48, v49
	v_cvt_pk_bf16_f32 v45, v50, v51
	global_store_dwordx4 v[28:29], v[42:45], off
	v_cvt_pk_bf16_f32 v28, v52, v53
	global_store_dword v[54:55], v28, off offset:128
	v_cvt_pk_bf16_f32 v28, v56, v57
	global_store_dword v[54:55], v28, off offset:160
	s_waitcnt vmcnt(6)
	v_mov_b32_e32 v42, v112
	v_mov_b32_e32 v43, v113
	v_mov_b32_e32 v44, v114
	v_mov_b32_e32 v45, v115
	v_mov_b32_e32 v41, v110
	v_mov_b32_e32 v46, v111
	s_cbranch_scc1 .Lrope_nopf_k
	v_lshl_add_u64 v[14:15], v[14:15], 0, s[16:17]
	v_lshl_add_u64 v[16:17], v[16:17], 0, s[16:17]
	v_lshl_add_u64 v[122:123], v[14:15], 0, s[2:3]
	v_lshl_add_u64 v[122:123], v[122:123], 0, s[24:25]
	global_load_dword v110, v[122:123], off offset:800
	global_load_dword v111, v[122:123], off offset:768
	v_lshl_add_u64 v[124:125], v[16:17], 0, s[2:3]
	global_load_dwordx4 v[112:115], v[124:125], off
.Lrope_nopf_k:
	v_lshlrev_b32_e32 v54, 16, v41
	v_lshlrev_b32_e32 v28, 16, v46
	v_and_b32_e32 v29, 0xffff0000, v46
	v_and_b32_e32 v55, 0xffff0000, v41
	v_pk_mul_f32 v[72:73], v[28:29], v[28:29]
	v_pk_mul_f32 v[74:75], v[54:55], v[54:55]
	v_lshlrev_b32_e32 v64, 16, v42
	v_and_b32_e32 v65, 0xffff0000, v42
	v_add_f32_e32 v41, v74, v75
	v_add_f32_e32 v72, v72, v73
	v_lshlrev_b32_e32 v60, 16, v43
	v_and_b32_e32 v61, 0xffff0000, v43
	v_pk_mul_f32 v[42:43], v[64:65], v[64:65]
	v_add_f32_e32 v41, v72, v41
	v_add_f32_e32 v41, v41, v42
	v_pk_mul_f32 v[62:63], v[60:61], v[60:61]
	v_add_f32_e32 v41, v41, v43
	v_lshlrev_b32_e32 v70, 16, v44
	v_and_b32_e32 v71, 0xffff0000, v44
	v_add_f32_e32 v41, v41, v62
	v_lshlrev_b32_e32 v66, 16, v45
	v_and_b32_e32 v67, 0xffff0000, v45
	v_pk_mul_f32 v[44:45], v[70:71], v[70:71]
	v_add_f32_e32 v41, v41, v63
	v_add_f32_e32 v41, v41, v44
	v_pk_mul_f32 v[68:69], v[66:67], v[66:67]
	v_add_f32_e32 v41, v41, v45
	v_add_f32_e32 v41, v41, v68
	v_add_f32_e32 v41, v41, v69
	ds_bpermute_b32 v42, v36, v41
	s_waitcnt lgkmcnt(0)
	v_add_f32_e32 v41, v41, v42
	ds_bpermute_b32 v42, v37, v41
	s_waitcnt lgkmcnt(0)
	v_add_f32_e32 v41, v41, v42
	ds_bpermute_b32 v42, v38, v41
	s_waitcnt lgkmcnt(0)
	v_add_f32_e32 v41, v41, v42
	v_fmamk_f32 v41, v41, 0x3c2aaaab, v207
	v_rsq_f32_e32 v42, v41
	s_nop 0
	v_pk_mul_f32 v[44:45], v[92:93], v[42:43] op_sel_hi:[1,0]
	s_nop 0
	v_pk_mul_f32 v[28:29], v[44:45], v[28:29]
	v_pk_mul_f32 v[44:45], v[94:95], v[42:43] op_sel_hi:[1,0]
	s_nop 0
	v_pk_mul_f32 v[44:45], v[44:45], v[54:55]
	s_nop 0
	v_pk_mul_f32 v[54:55], v[18:19], v[44:45]
	s_nop 0
	v_pk_fma_f32 v[54:55], v[20:21], v[28:29], v[54:55]
	v_pk_mul_f32 v[20:21], v[20:21], v[44:45]
	s_nop 0
	v_pk_fma_f32 v[28:29], v[18:19], v[28:29], v[20:21] neg_lo:[0,0,1] neg_hi:[0,0,1]
	v_pk_mul_f32 v[18:19], v[42:43], v[70:71] op_sel_hi:[0,1]
	v_pk_mul_f32 v[20:21], v[100:101], v[18:19]
	v_pk_mul_f32 v[18:19], v[42:43], v[66:67] op_sel_hi:[0,1]
	v_pk_mul_f32 v[44:45], v[102:103], v[18:19]
	v_pk_mul_f32 v[18:19], v[42:43], v[64:65] op_sel_hi:[0,1]
	v_pk_mul_f32 v[42:43], v[42:43], v[60:61] op_sel_hi:[0,1]
	v_pk_mul_f32 v[18:19], v[96:97], v[18:19]
	v_pk_mul_f32 v[42:43], v[98:99], v[42:43]
	v_cvt_pk_bf16_f32 v18, v18, v19
	v_cvt_pk_bf16_f32 v19, v42, v43
	v_cvt_pk_bf16_f32 v20, v20, v21
	v_cvt_pk_bf16_f32 v21, v44, v45
	global_store_dwordx4 v[22:23], v[18:21], off
	s_nop 1
	v_cvt_pk_bf16_f32 v18, v28, v29
	global_store_dword v[24:25], v18, off
	v_cvt_pk_bf16_f32 v18, v54, v55
	global_store_dword v[26:27], v18, off
	s_cbranch_scc0 .LBB0_949

.LBB0_1177:
	s_waitcnt vmcnt(0)
	s_waitcnt vmcnt(0)
	s_barrier
	v_exp_f32_e32 v80, v48
	v_exp_f32_e32 v81, v49
	v_exp_f32_e32 v84, v56
	v_exp_f32_e32 v82, v50
	v_exp_f32_e32 v83, v51
	v_exp_f32_e32 v85, v52
	v_exp_f32_e32 v86, v53
	v_exp_f32_e32 v87, v54
	v_exp_f32_e32 v88, v55
	ds_read_b128 v[52:55], v173 offset:53248
	ds_read_b128 v[48:51], v173 offset:49152
	ds_read_b128 v[56:59], v197 offset:49152
	ds_read_b128 v[60:63], v197 offset:53248
	ds_read_b128 v[64:67], v193 offset:49152
	ds_read_b128 v[68:71], v193 offset:53248
	ds_read_b128 v[72:75], v195 offset:49152
	ds_read_b128 v[76:79], v195 offset:53248
	v_add_f32_e32 v32, v32, v80
	v_add_f32_e32 v33, v33, v81
	v_cvt_pk_bf16_f32 v80, v80, v81
	v_add_f32_e32 v34, v34, v82
	v_add_f32_e32 v35, v35, v83
	v_cvt_pk_bf16_f32 v81, v82, v83
	v_add_f32_e32 v32, v32, v85
	v_add_f32_e32 v33, v33, v86
	v_cvt_pk_bf16_f32 v82, v85, v86
	v_add_f32_e32 v34, v34, v87
	v_add_f32_e32 v35, v35, v88
	v_cvt_pk_bf16_f32 v83, v87, v88
	s_waitcnt lgkmcnt(7)
	s_nop 0
	v_mfma_f32_32x32x16_bf16 v[16:31], v[52:55], v[80:83], v[16:31]
	s_waitcnt lgkmcnt(6)
	v_mfma_f32_32x32x16_bf16 v[0:15], v[48:51], v[80:83], v[0:15]
	v_cvt_pk_bf16_f32 v48, v84, v84
	v_mov_b32_e32 v49, v48
	v_mov_b32_e32 v50, v48
	v_mov_b32_e32 v51, v48
	s_waitcnt lgkmcnt(4)
	s_nop 0
	v_mfma_f32_32x32x16_bf16 v[16:31], v[60:63], v[48:51], v[16:31]
	s_waitcnt lgkmcnt(2)
	v_mfma_f32_32x32x16_bf16 v[16:31], v[68:71], v[48:51], v[16:31]
	s_waitcnt lgkmcnt(0)
	v_mfma_f32_32x32x16_bf16 v[16:31], v[76:79], v[48:51], v[16:31]
	v_mfma_f32_32x32x16_bf16 v[0:15], v[56:59], v[48:51], v[0:15]
	v_mfma_f32_32x32x16_bf16 v[0:15], v[64:67], v[48:51], v[0:15]
	v_mfma_f32_32x32x16_bf16 v[0:15], v[72:75], v[48:51], v[0:15]
	s_nop 11
	v_add_f32_e32 v32, v32, v33
	v_add_f32_e32 v34, v34, v35
	v_add_f32_e32 v32, v32, v34
	ds_bpermute_b32 v33, v218, v32
	s_lshl_b32 s48, s59, 1
	v_mov_b32_e32 v169, v149
	s_waitcnt lgkmcnt(0)
	s_barrier
	v_add_f32_e32 v32, v32, v33
	v_div_scale_f32 v33, s[6:7], v32, v32, 1.0
	v_rcp_f32_e32 v34, v33
	v_div_scale_f32 v35, vcc, 1.0, v32, 1.0
	v_fma_f32 v36, -v33, v34, 1.0
	v_fmac_f32_e32 v34, v36, v34
	v_mul_f32_e32 v36, v35, v34
	v_fma_f32 v37, -v33, v36, v35
	v_fmac_f32_e32 v36, v37, v34
	v_fma_f32 v33, -v33, v36, v35
	v_div_fmas_f32 v33, v33, v34, v36
	v_div_fixup_f32 v32, v33, v32, 1.0
	v_lshlrev_b64 v[34:35], 10, v[170:171]
	v_lshl_add_u64 v[34:35], s[34:35], 0, v[34:35]
	v_pk_mul_f32 v[0:1], v[0:1], v[32:33] op_sel_hi:[1,0]
	v_pk_mul_f32 v[2:3], v[2:3], v[32:33] op_sel_hi:[1,0]
	v_lshl_add_u64 v[34:35], v[34:35], 0, s[48:49]
	v_cvt_pk_bf16_f32 v0, v0, v1
	v_cvt_pk_bf16_f32 v1, v2, v3
	v_pk_mul_f32 v[2:3], v[16:17], v[32:33] op_sel_hi:[1,0]
	v_pk_mul_f32 v[16:17], v[18:19], v[32:33] op_sel_hi:[1,0]
	v_lshl_add_u64 v[34:35], v[34:35], 0, v[168:169]
	v_cvt_pk_bf16_f32 v2, v2, v3
	v_cvt_pk_bf16_f32 v3, v16, v17
	global_store_dwordx2 v[34:35], v[0:1], off
	global_store_dwordx2 v[34:35], v[2:3], off offset:64
	v_pk_mul_f32 v[0:1], v[4:5], v[32:33] op_sel_hi:[1,0]
	v_pk_mul_f32 v[2:3], v[6:7], v[32:33] op_sel_hi:[1,0]
	v_cvt_pk_bf16_f32 v0, v0, v1
	v_cvt_pk_bf16_f32 v1, v2, v3
	v_pk_mul_f32 v[2:3], v[20:21], v[32:33] op_sel_hi:[1,0]
	v_pk_mul_f32 v[4:5], v[22:23], v[32:33] op_sel_hi:[1,0]
	v_cvt_pk_bf16_f32 v2, v2, v3
	v_cvt_pk_bf16_f32 v3, v4, v5
	global_store_dwordx2 v[34:35], v[0:1], off offset:16
	global_store_dwordx2 v[34:35], v[2:3], off offset:80
	v_pk_mul_f32 v[0:1], v[8:9], v[32:33] op_sel_hi:[1,0]
	v_pk_mul_f32 v[2:3], v[10:11], v[32:33] op_sel_hi:[1,0]
	v_cvt_pk_bf16_f32 v0, v0, v1
	v_cvt_pk_bf16_f32 v1, v2, v3
	v_pk_mul_f32 v[2:3], v[24:25], v[32:33] op_sel_hi:[1,0]
	v_pk_mul_f32 v[4:5], v[26:27], v[32:33] op_sel_hi:[1,0]
	v_cvt_pk_bf16_f32 v2, v2, v3
	v_cvt_pk_bf16_f32 v3, v4, v5
	global_store_dwordx2 v[34:35], v[0:1], off offset:32
	global_store_dwordx2 v[34:35], v[2:3], off offset:96
	v_pk_mul_f32 v[0:1], v[12:13], v[32:33] op_sel_hi:[1,0]
	v_pk_mul_f32 v[2:3], v[14:15], v[32:33] op_sel_hi:[1,0]
	v_cvt_pk_bf16_f32 v0, v0, v1
	v_cvt_pk_bf16_f32 v1, v2, v3
	v_pk_mul_f32 v[2:3], v[28:29], v[32:33] op_sel_hi:[1,0]
	v_pk_mul_f32 v[4:5], v[30:31], v[32:33] op_sel_hi:[1,0]
	s_add_i32 s58, s58, s82
	v_cvt_pk_bf16_f32 v2, v2, v3
	v_cvt_pk_bf16_f32 v3, v4, v5
	s_cmpk_gt_i32 s58, 0x3ff
	global_store_dwordx2 v[34:35], v[0:1], off offset:48
	global_store_dwordx2 v[34:35], v[2:3], off offset:112
	s_cbranch_scc1 .LBB0_1225

.LBB0_1193:
	s_mov_b64 s[14:15], 0x3600180
	s_add_i32 s17, s16, 0x12000
	v_lshl_add_u64 v[80:81], v[188:189], 0, s[14:15]
	s_mov_b32 m0, s17
	v_exp_f32_e32 v150, v64
	global_load_lds_dwordx4 v[80:81], off
	ds_read_b128 v[80:83], v199 offset:12288
	ds_read_b128 v[84:87], v199 offset:18432
	ds_read_b128 v[154:157], v200 offset:12288
	ds_read_b128 v[202:205], v200 offset:18432
	ds_read_b128 v[212:215], v199 offset:12352
	ds_read_b128 v[220:223], v199 offset:18496
	ds_read_b128 v[224:227], v200 offset:12352
	ds_read_b128 v[228:231], v200 offset:18496
	ds_read_b128 v[232:235], v199 offset:12416
	ds_read_b128 v[236:239], v199 offset:18560
	ds_read_b128 v[240:243], v200 offset:12416
	ds_read_b128 v[244:247], v200 offset:18560
	s_waitcnt lgkmcnt(0)
	v_mfma_f32_32x32x16_bf16 v[96:111], v[80:83], v[136:139], 0
	v_exp_f32_e32 v151, v65
	v_exp_f32_e32 v152, v48
	v_exp_f32_e32 v153, v49
	v_exp_f32_e32 v167, v50
	v_exp_f32_e32 v169, v51
	v_exp_f32_e32 v201, v69
	v_exp_f32_e32 v208, v52
	v_mfma_f32_32x32x16_bf16 v[80:95], v[84:87], v[136:139], 0
	v_exp_f32_e32 v209, v55
	v_exp_f32_e32 v219, v74
	v_mfma_f32_32x32x16_bf16 v[96:111], v[154:157], v[132:135], v[96:111]
	v_exp_f32_e32 v155, v66
	v_exp_f32_e32 v156, v67
	v_exp_f32_e32 v157, v68
	v_mfma_f32_32x32x16_bf16 v[96:111], v[212:215], v[128:131], v[96:111]
	v_exp_f32_e32 v212, v72
	v_exp_f32_e32 v213, v73
	v_exp_f32_e32 v214, v56
	v_exp_f32_e32 v215, v57
	v_mfma_f32_32x32x16_bf16 v[96:111], v[224:227], v[124:127], v[96:111]
	v_exp_f32_e32 v224, v77
	v_exp_f32_e32 v225, v60
	v_exp_f32_e32 v226, v61
	v_exp_f32_e32 v227, v78
	v_mfma_f32_32x32x16_bf16 v[96:111], v[232:235], v[120:123], v[96:111]
	v_mfma_f32_32x32x16_bf16 v[96:111], v[240:243], v[116:119], v[96:111]
	v_mfma_f32_32x32x16_bf16 v[80:95], v[202:205], v[132:135], v[80:95]
	v_exp_f32_e32 v202, v53
	v_exp_f32_e32 v203, v70
	v_exp_f32_e32 v204, v71
	v_exp_f32_e32 v205, v54
	v_mfma_f32_32x32x16_bf16 v[80:95], v[220:223], v[128:131], v[80:95]
	v_exp_f32_e32 v220, v75
	v_exp_f32_e32 v221, v58
	v_exp_f32_e32 v222, v59
	v_exp_f32_e32 v223, v76
	v_mfma_f32_32x32x16_bf16 v[80:95], v[228:231], v[124:127], v[80:95]
	v_exp_f32_e32 v228, v79
	v_exp_f32_e32 v229, v62
	v_exp_f32_e32 v230, v63
	v_mfma_f32_32x32x16_bf16 v[80:95], v[236:239], v[120:123], v[80:95]
	ds_read_b128 v[48:51], v173 offset:49152
	ds_read_b128 v[52:55], v173 offset:53248
	ds_read_b128 v[56:59], v197 offset:49152
	ds_read_b128 v[60:63], v197 offset:53248
	ds_read_b128 v[64:67], v193 offset:49152
	ds_read_b128 v[68:71], v193 offset:53248
	ds_read_b128 v[72:75], v195 offset:49152
	ds_read_b128 v[76:79], v195 offset:53248
	v_add_f32_e32 v32, v32, v150
	v_add_f32_e32 v33, v33, v151
	v_cvt_pk_bf16_f32 v154, v150, v151
	v_add_f32_e32 v34, v34, v155
	v_add_f32_e32 v35, v35, v156
	v_cvt_pk_bf16_f32 v155, v155, v156
	v_add_f32_e32 v32, v32, v157
	v_add_f32_e32 v33, v33, v201
	v_cvt_pk_bf16_f32 v156, v157, v201
	v_add_f32_e32 v34, v34, v203
	v_add_f32_e32 v35, v35, v204
	v_cvt_pk_bf16_f32 v157, v203, v204
	v_mfma_f32_32x32x16_bf16 v[80:95], v[244:247], v[116:119], v[80:95]
	s_and_b64 vcc, exec, s[6:7]
	s_waitcnt lgkmcnt(0)
	v_mfma_f32_32x32x16_bf16 v[16:31], v[52:55], v[154:157], v[16:31]
	v_mfma_f32_32x32x16_bf16 v[0:15], v[48:51], v[154:157], v[0:15]
	v_add_f32_e32 v32, v32, v212
	v_add_f32_e32 v33, v33, v213
	v_cvt_pk_bf16_f32 v48, v212, v213
	v_add_f32_e32 v34, v34, v219
	v_add_f32_e32 v35, v35, v220
	v_cvt_pk_bf16_f32 v49, v219, v220
	v_add_f32_e32 v32, v32, v223
	v_add_f32_e32 v33, v33, v224
	v_cvt_pk_bf16_f32 v50, v223, v224
	v_cvt_pk_bf16_f32 v51, v227, v228
	v_add_f32_e32 v34, v34, v227
	v_add_f32_e32 v35, v35, v228
	v_mfma_f32_32x32x16_bf16 v[16:31], v[60:63], v[48:51], v[16:31]
	v_mfma_f32_32x32x16_bf16 v[0:15], v[56:59], v[48:51], v[0:15]
	v_add_f32_e32 v32, v32, v152
	v_add_f32_e32 v33, v33, v153
	v_cvt_pk_bf16_f32 v52, v152, v153
	v_add_f32_e32 v34, v34, v167
	v_add_f32_e32 v35, v35, v169
	v_cvt_pk_bf16_f32 v53, v167, v169
	v_add_f32_e32 v32, v32, v208
	v_add_f32_e32 v33, v33, v202
	v_cvt_pk_bf16_f32 v54, v208, v202
	v_cvt_pk_bf16_f32 v55, v205, v209
	v_add_f32_e32 v34, v34, v205
	v_add_f32_e32 v35, v35, v209
	v_mfma_f32_32x32x16_bf16 v[16:31], v[68:71], v[52:55], v[16:31]
	v_mfma_f32_32x32x16_bf16 v[0:15], v[64:67], v[52:55], v[0:15]
	v_add_f32_e32 v32, v32, v214
	v_add_f32_e32 v33, v33, v215
	v_cvt_pk_bf16_f32 v48, v214, v215
	v_add_f32_e32 v34, v34, v221
	v_add_f32_e32 v35, v35, v222
	v_cvt_pk_bf16_f32 v49, v221, v222
	v_add_f32_e32 v32, v32, v225
	v_add_f32_e32 v33, v33, v226
	v_cvt_pk_bf16_f32 v50, v225, v226
	v_cvt_pk_bf16_f32 v51, v229, v230
	v_add_f32_e32 v34, v34, v229
	v_add_f32_e32 v35, v35, v230
	v_mfma_f32_32x32x16_bf16 v[16:31], v[76:79], v[48:51], v[16:31]
	v_mfma_f32_32x32x16_bf16 v[0:15], v[72:75], v[48:51], v[0:15]
	s_cbranch_vccnz .LBB0_1196
	v_pk_add_f32 v[102:103], v[102:103], v[172:173] op_sel_hi:[1,0] neg_lo:[0,1] neg_hi:[0,1]
	v_pk_add_f32 v[110:111], v[110:111], v[172:173] op_sel_hi:[1,0] neg_lo:[0,1] neg_hi:[0,1]
	v_pk_add_f32 v[96:97], v[96:97], v[172:173] op_sel_hi:[1,0] neg_lo:[0,1] neg_hi:[0,1]
	v_pk_add_f32 v[98:99], v[98:99], v[172:173] op_sel_hi:[1,0] neg_lo:[0,1] neg_hi:[0,1]
	v_pk_add_f32 v[100:101], v[100:101], v[172:173] op_sel_hi:[1,0] neg_lo:[0,1] neg_hi:[0,1]
	v_pk_add_f32 v[104:105], v[104:105], v[172:173] op_sel_hi:[1,0] neg_lo:[0,1] neg_hi:[0,1]
	v_pk_add_f32 v[106:107], v[106:107], v[172:173] op_sel_hi:[1,0] neg_lo:[0,1] neg_hi:[0,1]
	v_pk_add_f32 v[108:109], v[108:109], v[172:173] op_sel_hi:[1,0] neg_lo:[0,1] neg_hi:[0,1]
	v_pk_add_f32 v[94:95], v[94:95], v[172:173] op_sel_hi:[1,0] neg_lo:[0,1] neg_hi:[0,1]
	v_max_f32_e32 v50, v102, v103
	v_max_f32_e32 v53, v110, v111
	v_pk_add_f32 v[82:83], v[82:83], v[172:173] op_sel_hi:[1,0] neg_lo:[0,1] neg_hi:[0,1]
	v_pk_add_f32 v[86:87], v[86:87], v[172:173] op_sel_hi:[1,0] neg_lo:[0,1] neg_hi:[0,1]
	v_pk_add_f32 v[88:89], v[88:89], v[172:173] op_sel_hi:[1,0] neg_lo:[0,1] neg_hi:[0,1]
	v_pk_add_f32 v[90:91], v[90:91], v[172:173] op_sel_hi:[1,0] neg_lo:[0,1] neg_hi:[0,1]
	v_pk_add_f32 v[92:93], v[92:93], v[172:173] op_sel_hi:[1,0] neg_lo:[0,1] neg_hi:[0,1]
	v_max_f32_e32 v48, v96, v97
	v_max_f32_e32 v49, v98, v99
	v_max3_f32 v50, v100, v101, v50
	v_max_f32_e32 v51, v104, v105
	v_max_f32_e32 v52, v106, v107
	v_max3_f32 v53, v108, v109, v53
	v_max_f32_e32 v54, v94, v95
	v_pk_add_f32 v[80:81], v[80:81], v[172:173] op_sel_hi:[1,0] neg_lo:[0,1] neg_hi:[0,1]
	v_pk_add_f32 v[84:85], v[84:85], v[172:173] op_sel_hi:[1,0] neg_lo:[0,1] neg_hi:[0,1]
	v_max3_f32 v48, v48, v49, v50
	v_max3_f32 v49, v51, v52, v53
	v_max_f32_e32 v50, v82, v83
	v_max_f32_e32 v51, v86, v87
	v_max_f32_e32 v52, v88, v89
	v_max_f32_e32 v53, v90, v91
	v_max3_f32 v54, v92, v93, v54
	v_max3_f32 v50, v80, v81, v50
	v_max3_f32 v51, v84, v85, v51
	v_max3_f32 v52, v52, v53, v54
	v_max3_f32 v50, v50, v51, v52
	v_max3_f32 v48, v48, v49, v50
	ds_bpermute_b32 v49, v218, v48
	s_mov_b32 s14, 0x41000000
	s_waitcnt lgkmcnt(0)
	v_max_f32_e32 v49, v49, v49
	v_max_f32_e32 v48, v48, v49
	v_cmp_lt_f32_e32 vcc, s14, v48
	s_cbranch_vccz .LBB0_1196
	v_max_f32_e32 v48, v48, v48
	v_max_f32_e32 v49, 0, v48
	v_exp_f32_e64 v48, -v49
	v_sub_f32_e32 v96, v96, v49
	v_sub_f32_e32 v97, v97, v49
	v_sub_f32_e32 v98, v98, v49
	v_sub_f32_e32 v99, v99, v49
	v_sub_f32_e32 v100, v100, v49
	v_sub_f32_e32 v101, v101, v49
	v_sub_f32_e32 v102, v102, v49
	v_sub_f32_e32 v103, v103, v49
	v_sub_f32_e32 v104, v104, v49
	v_sub_f32_e32 v105, v105, v49
	v_sub_f32_e32 v106, v106, v49
	v_sub_f32_e32 v107, v107, v49
	v_sub_f32_e32 v108, v108, v49
	v_sub_f32_e32 v109, v109, v49
	v_sub_f32_e32 v110, v110, v49
	v_sub_f32_e32 v111, v111, v49
	v_sub_f32_e32 v80, v80, v49
	v_sub_f32_e32 v81, v81, v49
	v_sub_f32_e32 v82, v82, v49
	v_sub_f32_e32 v83, v83, v49
	v_sub_f32_e32 v84, v84, v49
	v_sub_f32_e32 v85, v85, v49
	v_sub_f32_e32 v86, v86, v49
	v_sub_f32_e32 v87, v87, v49
	v_sub_f32_e32 v88, v88, v49
	v_sub_f32_e32 v89, v89, v49
	v_sub_f32_e32 v90, v90, v49
	v_sub_f32_e32 v91, v91, v49
	v_sub_f32_e32 v92, v92, v49
	v_sub_f32_e32 v93, v93, v49
	v_sub_f32_e32 v94, v94, v49
	v_sub_f32_e32 v95, v95, v49
	v_pk_mul_f32 v[14:15], v[14:15], v[48:49] op_sel_hi:[1,0]
	v_pk_mul_f32 v[12:13], v[12:13], v[48:49] op_sel_hi:[1,0]
	v_pk_mul_f32 v[10:11], v[10:11], v[48:49] op_sel_hi:[1,0]
	v_pk_mul_f32 v[8:9], v[8:9], v[48:49] op_sel_hi:[1,0]
	v_pk_mul_f32 v[6:7], v[6:7], v[48:49] op_sel_hi:[1,0]
	v_pk_mul_f32 v[4:5], v[4:5], v[48:49] op_sel_hi:[1,0]
	v_pk_mul_f32 v[2:3], v[2:3], v[48:49] op_sel_hi:[1,0]
	v_pk_mul_f32 v[0:1], v[0:1], v[48:49] op_sel_hi:[1,0]
	v_pk_mul_f32 v[30:31], v[30:31], v[48:49] op_sel_hi:[1,0]
	v_pk_mul_f32 v[28:29], v[28:29], v[48:49] op_sel_hi:[1,0]
	v_pk_mul_f32 v[26:27], v[26:27], v[48:49] op_sel_hi:[1,0]
	v_pk_mul_f32 v[24:25], v[24:25], v[48:49] op_sel_hi:[1,0]
	v_pk_mul_f32 v[22:23], v[22:23], v[48:49] op_sel_hi:[1,0]
	v_pk_mul_f32 v[20:21], v[20:21], v[48:49] op_sel_hi:[1,0]
	v_pk_mul_f32 v[18:19], v[18:19], v[48:49] op_sel_hi:[1,0]
	v_pk_mul_f32 v[16:17], v[16:17], v[48:49] op_sel_hi:[1,0]
	v_pk_mul_f32 v[46:47], v[46:47], v[48:49] op_sel_hi:[1,0]
	v_pk_mul_f32 v[44:45], v[44:45], v[48:49] op_sel_hi:[1,0]
	v_pk_mul_f32 v[42:43], v[42:43], v[48:49] op_sel_hi:[1,0]
	v_pk_mul_f32 v[40:41], v[40:41], v[48:49] op_sel_hi:[1,0]
	v_pk_mul_f32 v[38:39], v[38:39], v[48:49] op_sel_hi:[1,0]
	v_pk_mul_f32 v[36:37], v[36:37], v[48:49] op_sel_hi:[1,0]
	v_pk_mul_f32 v[34:35], v[34:35], v[48:49] op_sel_hi:[1,0]
	v_pk_mul_f32 v[32:33], v[32:33], v[48:49] op_sel_hi:[1,0]
	v_add_f32_e32 v172, v172, v49
.LBB0_1196:
	ds_read_b128 v[48:51], v199 offset:24576
	ds_read_b128 v[52:55], v199 offset:30720
	ds_read_b128 v[154:157], v200 offset:24576
	ds_read_b128 v[202:205], v200 offset:30720
	ds_read_b128 v[212:215], v199 offset:24640
	ds_read_b128 v[220:223], v199 offset:30784
	ds_read_b128 v[224:227], v200 offset:24640
	ds_read_b128 v[228:231], v200 offset:30784
	ds_read_b128 v[232:235], v199 offset:24704
	ds_read_b128 v[236:239], v199 offset:30848
	ds_read_b128 v[240:243], v200 offset:24704
	ds_read_b128 v[244:247], v200 offset:30848
	s_waitcnt lgkmcnt(0)
	v_mfma_f32_32x32x16_bf16 v[64:79], v[48:51], v[136:139], 0
	v_exp_f32_e32 v150, v96
	v_exp_f32_e32 v151, v97
	v_exp_f32_e32 v152, v80
	v_exp_f32_e32 v153, v81
	v_exp_f32_e32 v167, v82
	v_exp_f32_e32 v169, v83
	v_exp_f32_e32 v201, v101
	v_mfma_f32_32x32x16_bf16 v[48:63], v[52:55], v[136:139], 0
	v_exp_f32_e32 v208, v84
	v_exp_f32_e32 v209, v87
	v_exp_f32_e32 v219, v106
	v_mfma_f32_32x32x16_bf16 v[64:79], v[154:157], v[132:135], v[64:79]
	v_exp_f32_e32 v155, v98
	v_exp_f32_e32 v156, v99
	v_exp_f32_e32 v157, v100
	v_mfma_f32_32x32x16_bf16 v[64:79], v[212:215], v[128:131], v[64:79]
	v_exp_f32_e32 v212, v104
	v_exp_f32_e32 v213, v105
	v_exp_f32_e32 v214, v88
	v_exp_f32_e32 v215, v89
	v_mfma_f32_32x32x16_bf16 v[64:79], v[224:227], v[124:127], v[64:79]
	v_exp_f32_e32 v224, v109
	v_exp_f32_e32 v225, v92
	v_exp_f32_e32 v226, v93
	v_exp_f32_e32 v227, v110
	v_mfma_f32_32x32x16_bf16 v[64:79], v[232:235], v[120:123], v[64:79]
	v_mfma_f32_32x32x16_bf16 v[64:79], v[240:243], v[116:119], v[64:79]
	v_mfma_f32_32x32x16_bf16 v[48:63], v[202:205], v[132:135], v[48:63]
	v_exp_f32_e32 v202, v85
	v_exp_f32_e32 v203, v102
	v_exp_f32_e32 v204, v103
	v_exp_f32_e32 v205, v86
	v_mfma_f32_32x32x16_bf16 v[48:63], v[220:223], v[128:131], v[48:63]
	v_exp_f32_e32 v220, v107
	v_exp_f32_e32 v221, v90
	v_exp_f32_e32 v222, v91
	v_exp_f32_e32 v223, v108
	v_mfma_f32_32x32x16_bf16 v[48:63], v[228:231], v[124:127], v[48:63]
	v_exp_f32_e32 v228, v111
	v_exp_f32_e32 v229, v94
	v_exp_f32_e32 v230, v95
	v_mfma_f32_32x32x16_bf16 v[48:63], v[236:239], v[120:123], v[48:63]
	ds_read_b128 v[80:83], v173 offset:57344
	ds_read_b128 v[84:87], v173 offset:61440
	ds_read_b128 v[88:91], v197 offset:57344
	ds_read_b128 v[92:95], v197 offset:61440
	ds_read_b128 v[96:99], v193 offset:57344
	ds_read_b128 v[100:103], v193 offset:61440
	ds_read_b128 v[104:107], v195 offset:57344
	ds_read_b128 v[108:111], v195 offset:61440
	v_add_f32_e32 v32, v32, v150
	v_add_f32_e32 v33, v33, v151
	v_cvt_pk_bf16_f32 v154, v150, v151
	v_add_f32_e32 v34, v34, v155
	v_add_f32_e32 v35, v35, v156
	v_cvt_pk_bf16_f32 v155, v155, v156
	v_add_f32_e32 v32, v32, v157
	v_add_f32_e32 v33, v33, v201
	v_cvt_pk_bf16_f32 v156, v157, v201
	v_add_f32_e32 v34, v34, v203
	v_add_f32_e32 v35, v35, v204
	v_cvt_pk_bf16_f32 v157, v203, v204
	v_mfma_f32_32x32x16_bf16 v[48:63], v[244:247], v[116:119], v[48:63]
	s_and_b64 vcc, exec, s[6:7]
	s_waitcnt lgkmcnt(0)
	v_mfma_f32_32x32x16_bf16 v[16:31], v[84:87], v[154:157], v[16:31]
	v_mfma_f32_32x32x16_bf16 v[0:15], v[80:83], v[154:157], v[0:15]
	v_add_f32_e32 v32, v32, v212
	v_add_f32_e32 v33, v33, v213
	v_cvt_pk_bf16_f32 v80, v212, v213
	v_add_f32_e32 v34, v34, v219
	v_add_f32_e32 v35, v35, v220
	v_cvt_pk_bf16_f32 v81, v219, v220
	v_add_f32_e32 v32, v32, v223
	v_add_f32_e32 v33, v33, v224
	v_cvt_pk_bf16_f32 v82, v223, v224
	v_cvt_pk_bf16_f32 v83, v227, v228
	v_add_f32_e32 v34, v34, v227
	v_add_f32_e32 v35, v35, v228
	v_mfma_f32_32x32x16_bf16 v[16:31], v[92:95], v[80:83], v[16:31]
	v_mfma_f32_32x32x16_bf16 v[0:15], v[88:91], v[80:83], v[0:15]
	v_add_f32_e32 v32, v32, v152
	v_add_f32_e32 v33, v33, v153
	v_cvt_pk_bf16_f32 v84, v152, v153
	v_add_f32_e32 v34, v34, v167
	v_add_f32_e32 v35, v35, v169
	v_cvt_pk_bf16_f32 v85, v167, v169
	v_add_f32_e32 v32, v32, v208
	v_add_f32_e32 v33, v33, v202
	v_cvt_pk_bf16_f32 v86, v208, v202
	v_cvt_pk_bf16_f32 v87, v205, v209
	v_add_f32_e32 v34, v34, v205
	v_add_f32_e32 v35, v35, v209
	v_mfma_f32_32x32x16_bf16 v[16:31], v[100:103], v[84:87], v[16:31]
	v_mfma_f32_32x32x16_bf16 v[0:15], v[96:99], v[84:87], v[0:15]
	v_add_f32_e32 v32, v32, v214
	v_add_f32_e32 v33, v33, v215
	v_cvt_pk_bf16_f32 v80, v214, v215
	v_add_f32_e32 v34, v34, v221
	v_add_f32_e32 v35, v35, v222
	v_cvt_pk_bf16_f32 v81, v221, v222
	v_add_f32_e32 v32, v32, v225
	v_add_f32_e32 v33, v33, v226
	v_cvt_pk_bf16_f32 v82, v225, v226
	v_cvt_pk_bf16_f32 v83, v229, v230
	v_add_f32_e32 v34, v34, v229
	v_add_f32_e32 v35, v35, v230
	v_mfma_f32_32x32x16_bf16 v[16:31], v[108:111], v[80:83], v[16:31]
	v_mfma_f32_32x32x16_bf16 v[0:15], v[104:107], v[80:83], v[0:15]
	s_cbranch_vccnz .LBB0_1199
	v_pk_add_f32 v[70:71], v[70:71], v[172:173] op_sel_hi:[1,0] neg_lo:[0,1] neg_hi:[0,1]
	v_pk_add_f32 v[78:79], v[78:79], v[172:173] op_sel_hi:[1,0] neg_lo:[0,1] neg_hi:[0,1]
	v_pk_add_f32 v[64:65], v[64:65], v[172:173] op_sel_hi:[1,0] neg_lo:[0,1] neg_hi:[0,1]
	v_pk_add_f32 v[66:67], v[66:67], v[172:173] op_sel_hi:[1,0] neg_lo:[0,1] neg_hi:[0,1]
	v_pk_add_f32 v[68:69], v[68:69], v[172:173] op_sel_hi:[1,0] neg_lo:[0,1] neg_hi:[0,1]
	v_pk_add_f32 v[72:73], v[72:73], v[172:173] op_sel_hi:[1,0] neg_lo:[0,1] neg_hi:[0,1]
	v_pk_add_f32 v[74:75], v[74:75], v[172:173] op_sel_hi:[1,0] neg_lo:[0,1] neg_hi:[0,1]
	v_pk_add_f32 v[76:77], v[76:77], v[172:173] op_sel_hi:[1,0] neg_lo:[0,1] neg_hi:[0,1]
	v_pk_add_f32 v[62:63], v[62:63], v[172:173] op_sel_hi:[1,0] neg_lo:[0,1] neg_hi:[0,1]
	v_max_f32_e32 v82, v70, v71
	v_max_f32_e32 v85, v78, v79
	v_pk_add_f32 v[50:51], v[50:51], v[172:173] op_sel_hi:[1,0] neg_lo:[0,1] neg_hi:[0,1]
	v_pk_add_f32 v[54:55], v[54:55], v[172:173] op_sel_hi:[1,0] neg_lo:[0,1] neg_hi:[0,1]
	v_pk_add_f32 v[56:57], v[56:57], v[172:173] op_sel_hi:[1,0] neg_lo:[0,1] neg_hi:[0,1]
	v_pk_add_f32 v[58:59], v[58:59], v[172:173] op_sel_hi:[1,0] neg_lo:[0,1] neg_hi:[0,1]
	v_pk_add_f32 v[60:61], v[60:61], v[172:173] op_sel_hi:[1,0] neg_lo:[0,1] neg_hi:[0,1]
	v_max_f32_e32 v80, v64, v65
	v_max_f32_e32 v81, v66, v67
	v_max3_f32 v82, v68, v69, v82
	v_max_f32_e32 v83, v72, v73
	v_max_f32_e32 v84, v74, v75
	v_max3_f32 v85, v76, v77, v85
	v_max_f32_e32 v86, v62, v63
	v_pk_add_f32 v[48:49], v[48:49], v[172:173] op_sel_hi:[1,0] neg_lo:[0,1] neg_hi:[0,1]
	v_pk_add_f32 v[52:53], v[52:53], v[172:173] op_sel_hi:[1,0] neg_lo:[0,1] neg_hi:[0,1]
	v_max3_f32 v80, v80, v81, v82
	v_max3_f32 v81, v83, v84, v85
	v_max_f32_e32 v82, v50, v51
	v_max_f32_e32 v83, v54, v55
	v_max_f32_e32 v84, v56, v57
	v_max_f32_e32 v85, v58, v59
	v_max3_f32 v86, v60, v61, v86
	v_max3_f32 v82, v48, v49, v82
	v_max3_f32 v83, v52, v53, v83
	v_max3_f32 v84, v84, v85, v86
	v_max3_f32 v82, v82, v83, v84
	v_max3_f32 v80, v80, v81, v82
	ds_bpermute_b32 v81, v218, v80
	s_mov_b32 s14, 0x41000000
	s_waitcnt lgkmcnt(0)
	v_max_f32_e32 v81, v81, v81
	v_max_f32_e32 v80, v80, v81
	v_cmp_lt_f32_e32 vcc, s14, v80
	s_cbranch_vccz .LBB0_1199
	v_max_f32_e32 v80, v80, v80
	v_max_f32_e32 v81, 0, v80
	v_exp_f32_e64 v80, -v81
	v_sub_f32_e32 v64, v64, v81
	v_sub_f32_e32 v65, v65, v81
	v_sub_f32_e32 v66, v66, v81
	v_sub_f32_e32 v67, v67, v81
	v_sub_f32_e32 v68, v68, v81
	v_sub_f32_e32 v69, v69, v81
	v_sub_f32_e32 v70, v70, v81
	v_sub_f32_e32 v71, v71, v81
	v_sub_f32_e32 v72, v72, v81
	v_sub_f32_e32 v73, v73, v81
	v_sub_f32_e32 v74, v74, v81
	v_sub_f32_e32 v75, v75, v81
	v_sub_f32_e32 v76, v76, v81
	v_sub_f32_e32 v77, v77, v81
	v_sub_f32_e32 v78, v78, v81
	v_sub_f32_e32 v79, v79, v81
	v_sub_f32_e32 v48, v48, v81
	v_sub_f32_e32 v49, v49, v81
	v_sub_f32_e32 v50, v50, v81
	v_sub_f32_e32 v51, v51, v81
	v_sub_f32_e32 v52, v52, v81
	v_sub_f32_e32 v53, v53, v81
	v_sub_f32_e32 v54, v54, v81
	v_sub_f32_e32 v55, v55, v81
	v_sub_f32_e32 v56, v56, v81
	v_sub_f32_e32 v57, v57, v81
	v_sub_f32_e32 v58, v58, v81
	v_sub_f32_e32 v59, v59, v81
	v_sub_f32_e32 v60, v60, v81
	v_sub_f32_e32 v61, v61, v81
	v_sub_f32_e32 v62, v62, v81
	v_sub_f32_e32 v63, v63, v81
	v_pk_mul_f32 v[14:15], v[14:15], v[80:81] op_sel_hi:[1,0]
	v_pk_mul_f32 v[12:13], v[12:13], v[80:81] op_sel_hi:[1,0]
	v_pk_mul_f32 v[10:11], v[10:11], v[80:81] op_sel_hi:[1,0]
	v_pk_mul_f32 v[8:9], v[8:9], v[80:81] op_sel_hi:[1,0]
	v_pk_mul_f32 v[6:7], v[6:7], v[80:81] op_sel_hi:[1,0]
	v_pk_mul_f32 v[4:5], v[4:5], v[80:81] op_sel_hi:[1,0]
	v_pk_mul_f32 v[2:3], v[2:3], v[80:81] op_sel_hi:[1,0]
	v_pk_mul_f32 v[0:1], v[0:1], v[80:81] op_sel_hi:[1,0]
	v_pk_mul_f32 v[30:31], v[30:31], v[80:81] op_sel_hi:[1,0]
	v_pk_mul_f32 v[28:29], v[28:29], v[80:81] op_sel_hi:[1,0]
	v_pk_mul_f32 v[26:27], v[26:27], v[80:81] op_sel_hi:[1,0]
	v_pk_mul_f32 v[24:25], v[24:25], v[80:81] op_sel_hi:[1,0]
	v_pk_mul_f32 v[22:23], v[22:23], v[80:81] op_sel_hi:[1,0]
	v_pk_mul_f32 v[20:21], v[20:21], v[80:81] op_sel_hi:[1,0]
	v_pk_mul_f32 v[18:19], v[18:19], v[80:81] op_sel_hi:[1,0]
	v_pk_mul_f32 v[16:17], v[16:17], v[80:81] op_sel_hi:[1,0]
	v_pk_mul_f32 v[46:47], v[46:47], v[80:81] op_sel_hi:[1,0]
	v_pk_mul_f32 v[44:45], v[44:45], v[80:81] op_sel_hi:[1,0]
	v_pk_mul_f32 v[42:43], v[42:43], v[80:81] op_sel_hi:[1,0]
	v_pk_mul_f32 v[40:41], v[40:41], v[80:81] op_sel_hi:[1,0]
	v_pk_mul_f32 v[38:39], v[38:39], v[80:81] op_sel_hi:[1,0]
	v_pk_mul_f32 v[36:37], v[36:37], v[80:81] op_sel_hi:[1,0]
	v_pk_mul_f32 v[34:35], v[34:35], v[80:81] op_sel_hi:[1,0]
	v_pk_mul_f32 v[32:33], v[32:33], v[80:81] op_sel_hi:[1,0]
	v_add_f32_e32 v172, v172, v81

.LBB0_1203:
	s_mov_b32 m0, s14
	s_mov_b64 s[14:15], 0x3600280
	global_load_lds_dwordx4 v[82:83], off
	v_lshl_add_u64 v[80:81], v[188:189], 0, s[14:15]
	s_mov_b32 m0, s62
	v_exp_f32_e32 v150, v64
	global_load_lds_dwordx4 v[80:81], off
	ds_read_b128 v[80:83], v199 offset:36864
	ds_read_b128 v[84:87], v199 offset:43008
	ds_read_b128 v[154:157], v200 offset:36864
	ds_read_b128 v[186:189], v200 offset:43008
	ds_read_b128 v[202:205], v199 offset:36928
	ds_read_b128 v[212:215], v199 offset:43072
	ds_read_b128 v[220:223], v200 offset:36928
	ds_read_b128 v[224:227], v200 offset:43072
	ds_read_b128 v[228:231], v199 offset:36992
	ds_read_b128 v[232:235], v199 offset:43136
	ds_read_b128 v[236:239], v200 offset:36992
	ds_read_b128 v[240:243], v200 offset:43136
	s_waitcnt lgkmcnt(0)
	v_mfma_f32_32x32x16_bf16 v[96:111], v[80:83], v[136:139], 0
	v_exp_f32_e32 v151, v65
	v_exp_f32_e32 v152, v48
	v_exp_f32_e32 v153, v49
	v_exp_f32_e32 v167, v50
	v_exp_f32_e32 v169, v51
	v_exp_f32_e32 v190, v69
	v_exp_f32_e32 v191, v52
	v_mfma_f32_32x32x16_bf16 v[80:95], v[84:87], v[136:139], 0
	v_exp_f32_e32 v201, v55
	v_exp_f32_e32 v208, v74
	v_exp_f32_e32 v209, v75
	v_exp_f32_e32 v219, v60
	v_mfma_f32_32x32x16_bf16 v[96:111], v[154:157], v[132:135], v[96:111]
	v_exp_f32_e32 v155, v66
	v_exp_f32_e32 v156, v67
	v_exp_f32_e32 v157, v68
	v_mfma_f32_32x32x16_bf16 v[96:111], v[202:205], v[128:131], v[96:111]
	v_exp_f32_e32 v202, v72
	v_exp_f32_e32 v203, v73
	v_exp_f32_e32 v204, v56
	v_exp_f32_e32 v205, v57
	v_mfma_f32_32x32x16_bf16 v[96:111], v[220:223], v[124:127], v[96:111]
	v_exp_f32_e32 v220, v61
	v_exp_f32_e32 v221, v78
	v_exp_f32_e32 v222, v79
	v_exp_f32_e32 v223, v62
	v_mfma_f32_32x32x16_bf16 v[96:111], v[228:231], v[120:123], v[96:111]
	v_mfma_f32_32x32x16_bf16 v[96:111], v[236:239], v[116:119], v[96:111]
	v_mfma_f32_32x32x16_bf16 v[80:95], v[186:189], v[132:135], v[80:95]
	v_exp_f32_e32 v186, v53
	v_exp_f32_e32 v187, v70
	v_exp_f32_e32 v188, v71
	v_exp_f32_e32 v189, v54
	v_mfma_f32_32x32x16_bf16 v[80:95], v[212:215], v[128:131], v[80:95]
	v_exp_f32_e32 v212, v58
	v_exp_f32_e32 v213, v59
	v_exp_f32_e32 v214, v76
	v_exp_f32_e32 v215, v77
	v_mfma_f32_32x32x16_bf16 v[80:95], v[224:227], v[124:127], v[80:95]
	v_exp_f32_e32 v224, v63
	v_mfma_f32_32x32x16_bf16 v[80:95], v[232:235], v[120:123], v[80:95]
	ds_read_b128 v[48:51], v192 offset:16384
	ds_read_b128 v[52:55], v192 offset:20480
	ds_read_b128 v[56:59], v198 offset:16384
	ds_read_b128 v[60:63], v198 offset:20480
	ds_read_b128 v[64:67], v194 offset:16384
	ds_read_b128 v[68:71], v194 offset:20480
	ds_read_b128 v[72:75], v196 offset:16384
	ds_read_b128 v[76:79], v196 offset:20480
	v_add_f32_e32 v32, v32, v150
	v_add_f32_e32 v33, v33, v151
	v_cvt_pk_bf16_f32 v154, v150, v151
	v_add_f32_e32 v34, v34, v155
	v_add_f32_e32 v35, v35, v156
	v_cvt_pk_bf16_f32 v155, v155, v156
	v_add_f32_e32 v32, v32, v157
	v_add_f32_e32 v33, v33, v190
	v_cvt_pk_bf16_f32 v156, v157, v190
	v_add_f32_e32 v34, v34, v187
	v_add_f32_e32 v35, v35, v188
	v_cvt_pk_bf16_f32 v157, v187, v188
	v_mfma_f32_32x32x16_bf16 v[80:95], v[240:243], v[116:119], v[80:95]
	s_and_b64 vcc, exec, s[6:7]
	s_waitcnt lgkmcnt(0)
	v_mfma_f32_32x32x16_bf16 v[16:31], v[52:55], v[154:157], v[16:31]
	v_mfma_f32_32x32x16_bf16 v[0:15], v[48:51], v[154:157], v[0:15]
	v_add_f32_e32 v32, v32, v202
	v_add_f32_e32 v33, v33, v203
	v_cvt_pk_bf16_f32 v48, v202, v203
	v_add_f32_e32 v34, v34, v208
	v_add_f32_e32 v35, v35, v209
	v_cvt_pk_bf16_f32 v49, v208, v209
	v_add_f32_e32 v32, v32, v214
	v_add_f32_e32 v33, v33, v215
	v_cvt_pk_bf16_f32 v50, v214, v215
	v_cvt_pk_bf16_f32 v51, v221, v222
	v_add_f32_e32 v34, v34, v221
	v_add_f32_e32 v35, v35, v222
	v_mfma_f32_32x32x16_bf16 v[16:31], v[60:63], v[48:51], v[16:31]
	v_mfma_f32_32x32x16_bf16 v[0:15], v[56:59], v[48:51], v[0:15]
	v_add_f32_e32 v32, v32, v152
	v_add_f32_e32 v33, v33, v153
	v_cvt_pk_bf16_f32 v52, v152, v153
	v_add_f32_e32 v34, v34, v167
	v_add_f32_e32 v35, v35, v169
	v_cvt_pk_bf16_f32 v53, v167, v169
	v_add_f32_e32 v32, v32, v191
	v_add_f32_e32 v33, v33, v186
	v_cvt_pk_bf16_f32 v54, v191, v186
	v_cvt_pk_bf16_f32 v55, v189, v201
	v_add_f32_e32 v34, v34, v189
	v_add_f32_e32 v35, v35, v201
	v_mfma_f32_32x32x16_bf16 v[16:31], v[68:71], v[52:55], v[16:31]
	v_mfma_f32_32x32x16_bf16 v[0:15], v[64:67], v[52:55], v[0:15]
	v_add_f32_e32 v32, v32, v204
	v_add_f32_e32 v33, v33, v205
	v_cvt_pk_bf16_f32 v48, v204, v205
	v_add_f32_e32 v34, v34, v212
	v_add_f32_e32 v35, v35, v213
	v_cvt_pk_bf16_f32 v49, v212, v213
	v_add_f32_e32 v32, v32, v219
	v_add_f32_e32 v33, v33, v220
	v_cvt_pk_bf16_f32 v50, v219, v220
	v_cvt_pk_bf16_f32 v51, v223, v224
	v_add_f32_e32 v34, v34, v223
	v_add_f32_e32 v35, v35, v224
	v_mfma_f32_32x32x16_bf16 v[16:31], v[76:79], v[48:51], v[16:31]
	v_mfma_f32_32x32x16_bf16 v[0:15], v[72:75], v[48:51], v[0:15]
	s_cbranch_vccnz .LBB0_1206
	v_pk_add_f32 v[102:103], v[102:103], v[172:173] op_sel_hi:[1,0] neg_lo:[0,1] neg_hi:[0,1]
	v_pk_add_f32 v[110:111], v[110:111], v[172:173] op_sel_hi:[1,0] neg_lo:[0,1] neg_hi:[0,1]
	v_pk_add_f32 v[96:97], v[96:97], v[172:173] op_sel_hi:[1,0] neg_lo:[0,1] neg_hi:[0,1]
	v_pk_add_f32 v[98:99], v[98:99], v[172:173] op_sel_hi:[1,0] neg_lo:[0,1] neg_hi:[0,1]
	v_pk_add_f32 v[100:101], v[100:101], v[172:173] op_sel_hi:[1,0] neg_lo:[0,1] neg_hi:[0,1]
	v_pk_add_f32 v[104:105], v[104:105], v[172:173] op_sel_hi:[1,0] neg_lo:[0,1] neg_hi:[0,1]
	v_pk_add_f32 v[106:107], v[106:107], v[172:173] op_sel_hi:[1,0] neg_lo:[0,1] neg_hi:[0,1]
	v_pk_add_f32 v[108:109], v[108:109], v[172:173] op_sel_hi:[1,0] neg_lo:[0,1] neg_hi:[0,1]
	v_pk_add_f32 v[94:95], v[94:95], v[172:173] op_sel_hi:[1,0] neg_lo:[0,1] neg_hi:[0,1]
	v_max_f32_e32 v50, v102, v103
	v_max_f32_e32 v53, v110, v111
	v_pk_add_f32 v[82:83], v[82:83], v[172:173] op_sel_hi:[1,0] neg_lo:[0,1] neg_hi:[0,1]
	v_pk_add_f32 v[86:87], v[86:87], v[172:173] op_sel_hi:[1,0] neg_lo:[0,1] neg_hi:[0,1]
	v_pk_add_f32 v[88:89], v[88:89], v[172:173] op_sel_hi:[1,0] neg_lo:[0,1] neg_hi:[0,1]
	v_pk_add_f32 v[90:91], v[90:91], v[172:173] op_sel_hi:[1,0] neg_lo:[0,1] neg_hi:[0,1]
	v_pk_add_f32 v[92:93], v[92:93], v[172:173] op_sel_hi:[1,0] neg_lo:[0,1] neg_hi:[0,1]
	v_max_f32_e32 v48, v96, v97
	v_max_f32_e32 v49, v98, v99
	v_max3_f32 v50, v100, v101, v50
	v_max_f32_e32 v51, v104, v105
	v_max_f32_e32 v52, v106, v107
	v_max3_f32 v53, v108, v109, v53
	v_max_f32_e32 v54, v94, v95
	v_pk_add_f32 v[80:81], v[80:81], v[172:173] op_sel_hi:[1,0] neg_lo:[0,1] neg_hi:[0,1]
	v_pk_add_f32 v[84:85], v[84:85], v[172:173] op_sel_hi:[1,0] neg_lo:[0,1] neg_hi:[0,1]
	v_max3_f32 v48, v48, v49, v50
	v_max3_f32 v49, v51, v52, v53
	v_max_f32_e32 v50, v82, v83
	v_max_f32_e32 v51, v86, v87
	v_max_f32_e32 v52, v88, v89
	v_max_f32_e32 v53, v90, v91
	v_max3_f32 v54, v92, v93, v54
	v_max3_f32 v50, v80, v81, v50
	v_max3_f32 v51, v84, v85, v51
	v_max3_f32 v52, v52, v53, v54
	v_max3_f32 v50, v50, v51, v52
	v_max3_f32 v48, v48, v49, v50
	ds_bpermute_b32 v49, v218, v48
	s_mov_b32 s14, 0x41000000
	s_waitcnt lgkmcnt(0)
	v_max_f32_e32 v49, v49, v49
	v_max_f32_e32 v48, v48, v49
	v_cmp_lt_f32_e32 vcc, s14, v48
	s_cbranch_vccz .LBB0_1206
	v_max_f32_e32 v48, v48, v48
	v_max_f32_e32 v49, 0, v48
	v_exp_f32_e64 v48, -v49
	v_sub_f32_e32 v96, v96, v49
	v_sub_f32_e32 v97, v97, v49
	v_sub_f32_e32 v98, v98, v49
	v_sub_f32_e32 v99, v99, v49
	v_sub_f32_e32 v100, v100, v49
	v_sub_f32_e32 v101, v101, v49
	v_sub_f32_e32 v102, v102, v49
	v_sub_f32_e32 v103, v103, v49
	v_sub_f32_e32 v104, v104, v49
	v_sub_f32_e32 v105, v105, v49
	v_sub_f32_e32 v106, v106, v49
	v_sub_f32_e32 v107, v107, v49
	v_sub_f32_e32 v108, v108, v49
	v_sub_f32_e32 v109, v109, v49
	v_sub_f32_e32 v110, v110, v49
	v_sub_f32_e32 v111, v111, v49
	v_sub_f32_e32 v80, v80, v49
	v_sub_f32_e32 v81, v81, v49
	v_sub_f32_e32 v82, v82, v49
	v_sub_f32_e32 v83, v83, v49
	v_sub_f32_e32 v84, v84, v49
	v_sub_f32_e32 v85, v85, v49
	v_sub_f32_e32 v86, v86, v49
	v_sub_f32_e32 v87, v87, v49
	v_sub_f32_e32 v88, v88, v49
	v_sub_f32_e32 v89, v89, v49
	v_sub_f32_e32 v90, v90, v49
	v_sub_f32_e32 v91, v91, v49
	v_sub_f32_e32 v92, v92, v49
	v_sub_f32_e32 v93, v93, v49
	v_sub_f32_e32 v94, v94, v49
	v_sub_f32_e32 v95, v95, v49
	v_pk_mul_f32 v[14:15], v[14:15], v[48:49] op_sel_hi:[1,0]
	v_pk_mul_f32 v[12:13], v[12:13], v[48:49] op_sel_hi:[1,0]
	v_pk_mul_f32 v[10:11], v[10:11], v[48:49] op_sel_hi:[1,0]
	v_pk_mul_f32 v[8:9], v[8:9], v[48:49] op_sel_hi:[1,0]
	v_pk_mul_f32 v[6:7], v[6:7], v[48:49] op_sel_hi:[1,0]
	v_pk_mul_f32 v[4:5], v[4:5], v[48:49] op_sel_hi:[1,0]
	v_pk_mul_f32 v[2:3], v[2:3], v[48:49] op_sel_hi:[1,0]
	v_pk_mul_f32 v[0:1], v[0:1], v[48:49] op_sel_hi:[1,0]
	v_pk_mul_f32 v[30:31], v[30:31], v[48:49] op_sel_hi:[1,0]
	v_pk_mul_f32 v[28:29], v[28:29], v[48:49] op_sel_hi:[1,0]
	v_pk_mul_f32 v[26:27], v[26:27], v[48:49] op_sel_hi:[1,0]
	v_pk_mul_f32 v[24:25], v[24:25], v[48:49] op_sel_hi:[1,0]
	v_pk_mul_f32 v[22:23], v[22:23], v[48:49] op_sel_hi:[1,0]
	v_pk_mul_f32 v[20:21], v[20:21], v[48:49] op_sel_hi:[1,0]
	v_pk_mul_f32 v[18:19], v[18:19], v[48:49] op_sel_hi:[1,0]
	v_pk_mul_f32 v[16:17], v[16:17], v[48:49] op_sel_hi:[1,0]
	v_pk_mul_f32 v[46:47], v[46:47], v[48:49] op_sel_hi:[1,0]
	v_pk_mul_f32 v[44:45], v[44:45], v[48:49] op_sel_hi:[1,0]
	v_pk_mul_f32 v[42:43], v[42:43], v[48:49] op_sel_hi:[1,0]
	v_pk_mul_f32 v[40:41], v[40:41], v[48:49] op_sel_hi:[1,0]
	v_pk_mul_f32 v[38:39], v[38:39], v[48:49] op_sel_hi:[1,0]
	v_pk_mul_f32 v[36:37], v[36:37], v[48:49] op_sel_hi:[1,0]
	v_pk_mul_f32 v[34:35], v[34:35], v[48:49] op_sel_hi:[1,0]
	v_pk_mul_f32 v[32:33], v[32:33], v[48:49] op_sel_hi:[1,0]
	v_add_f32_e32 v172, v172, v49
.LBB0_1206:
	ds_read_b128 v[48:51], v199
	ds_read_b128 v[52:55], v199 offset:6144
	ds_read_b128 v[154:157], v200
	ds_read_b128 v[186:189], v200 offset:6144
	ds_read_b128 v[202:205], v199 offset:64
	ds_read_b128 v[212:215], v199 offset:6208
	ds_read_b128 v[220:223], v200 offset:64
	ds_read_b128 v[224:227], v200 offset:6208
	ds_read_b128 v[228:231], v199 offset:128
	ds_read_b128 v[232:235], v199 offset:6272
	ds_read_b128 v[236:239], v200 offset:128
	ds_read_b128 v[240:243], v200 offset:6272
	s_waitcnt lgkmcnt(0)
	v_mfma_f32_32x32x16_bf16 v[64:79], v[48:51], v[136:139], 0
	v_exp_f32_e32 v150, v96
	v_exp_f32_e32 v151, v97
	v_exp_f32_e32 v152, v80
	v_exp_f32_e32 v153, v81
	v_exp_f32_e32 v167, v82
	v_exp_f32_e32 v169, v83
	v_exp_f32_e32 v190, v101
	v_mfma_f32_32x32x16_bf16 v[48:63], v[52:55], v[136:139], 0
	v_exp_f32_e32 v191, v84
	v_exp_f32_e32 v201, v87
	v_exp_f32_e32 v208, v106
	v_exp_f32_e32 v209, v107
	v_exp_f32_e32 v219, v92
	v_mfma_f32_32x32x16_bf16 v[64:79], v[154:157], v[132:135], v[64:79]
	v_exp_f32_e32 v155, v98
	v_exp_f32_e32 v156, v99
	v_exp_f32_e32 v157, v100
	v_mfma_f32_32x32x16_bf16 v[64:79], v[202:205], v[128:131], v[64:79]
	v_exp_f32_e32 v202, v104
	v_exp_f32_e32 v203, v105
	v_exp_f32_e32 v204, v88
	v_exp_f32_e32 v205, v89
	v_mfma_f32_32x32x16_bf16 v[64:79], v[220:223], v[124:127], v[64:79]
	v_exp_f32_e32 v220, v93
	v_exp_f32_e32 v221, v110
	v_exp_f32_e32 v222, v111
	v_exp_f32_e32 v223, v94
	v_mfma_f32_32x32x16_bf16 v[64:79], v[228:231], v[120:123], v[64:79]
	v_mfma_f32_32x32x16_bf16 v[64:79], v[236:239], v[116:119], v[64:79]
	v_mfma_f32_32x32x16_bf16 v[48:63], v[186:189], v[132:135], v[48:63]
	v_exp_f32_e32 v186, v85
	v_exp_f32_e32 v187, v102
	v_exp_f32_e32 v188, v103
	v_exp_f32_e32 v189, v86
	v_mfma_f32_32x32x16_bf16 v[48:63], v[212:215], v[128:131], v[48:63]
	v_exp_f32_e32 v212, v90
	v_exp_f32_e32 v213, v91
	v_exp_f32_e32 v214, v108
	v_exp_f32_e32 v215, v109
	v_mfma_f32_32x32x16_bf16 v[48:63], v[224:227], v[124:127], v[48:63]
	v_exp_f32_e32 v224, v95
	v_mfma_f32_32x32x16_bf16 v[48:63], v[232:235], v[120:123], v[48:63]
	ds_read_b128 v[80:83], v192 offset:24576
	ds_read_b128 v[84:87], v192 offset:28672
	ds_read_b128 v[88:91], v198 offset:24576
	ds_read_b128 v[92:95], v198 offset:28672
	ds_read_b128 v[96:99], v194 offset:24576
	ds_read_b128 v[100:103], v194 offset:28672
	ds_read_b128 v[104:107], v196 offset:24576
	ds_read_b128 v[108:111], v196 offset:28672
	v_add_f32_e32 v32, v32, v150
	v_add_f32_e32 v33, v33, v151
	v_cvt_pk_bf16_f32 v154, v150, v151
	v_add_f32_e32 v34, v34, v155
	v_add_f32_e32 v35, v35, v156
	v_cvt_pk_bf16_f32 v155, v155, v156
	v_add_f32_e32 v32, v32, v157
	v_add_f32_e32 v33, v33, v190
	v_cvt_pk_bf16_f32 v156, v157, v190
	v_add_f32_e32 v34, v34, v187
	v_add_f32_e32 v35, v35, v188
	v_cvt_pk_bf16_f32 v157, v187, v188
	v_mfma_f32_32x32x16_bf16 v[48:63], v[240:243], v[116:119], v[48:63]
	s_and_b64 vcc, exec, s[6:7]
	s_waitcnt lgkmcnt(0)
	v_mfma_f32_32x32x16_bf16 v[16:31], v[84:87], v[154:157], v[16:31]
	v_mfma_f32_32x32x16_bf16 v[0:15], v[80:83], v[154:157], v[0:15]
	v_add_f32_e32 v32, v32, v202
	v_add_f32_e32 v33, v33, v203
	v_cvt_pk_bf16_f32 v80, v202, v203
	v_add_f32_e32 v34, v34, v208
	v_add_f32_e32 v35, v35, v209
	v_cvt_pk_bf16_f32 v81, v208, v209
	v_add_f32_e32 v32, v32, v214
	v_add_f32_e32 v33, v33, v215
	v_cvt_pk_bf16_f32 v82, v214, v215
	v_cvt_pk_bf16_f32 v83, v221, v222
	v_add_f32_e32 v34, v34, v221
	v_add_f32_e32 v35, v35, v222
	v_mfma_f32_32x32x16_bf16 v[16:31], v[92:95], v[80:83], v[16:31]
	v_mfma_f32_32x32x16_bf16 v[0:15], v[88:91], v[80:83], v[0:15]
	v_add_f32_e32 v32, v32, v152
	v_add_f32_e32 v33, v33, v153
	v_cvt_pk_bf16_f32 v84, v152, v153
	v_add_f32_e32 v34, v34, v167
	v_add_f32_e32 v35, v35, v169
	v_cvt_pk_bf16_f32 v85, v167, v169
	v_add_f32_e32 v32, v32, v191
	v_add_f32_e32 v33, v33, v186
	v_cvt_pk_bf16_f32 v86, v191, v186
	v_cvt_pk_bf16_f32 v87, v189, v201
	v_add_f32_e32 v34, v34, v189
	v_add_f32_e32 v35, v35, v201
	v_mfma_f32_32x32x16_bf16 v[16:31], v[100:103], v[84:87], v[16:31]
	v_mfma_f32_32x32x16_bf16 v[0:15], v[96:99], v[84:87], v[0:15]
	v_add_f32_e32 v32, v32, v204
	v_add_f32_e32 v33, v33, v205
	v_cvt_pk_bf16_f32 v80, v204, v205
	v_add_f32_e32 v34, v34, v212
	v_add_f32_e32 v35, v35, v213
	v_cvt_pk_bf16_f32 v81, v212, v213
	v_add_f32_e32 v32, v32, v219
	v_add_f32_e32 v33, v33, v220
	v_cvt_pk_bf16_f32 v82, v219, v220
	v_cvt_pk_bf16_f32 v83, v223, v224
	v_add_f32_e32 v34, v34, v223
	v_add_f32_e32 v35, v35, v224
	v_mfma_f32_32x32x16_bf16 v[16:31], v[108:111], v[80:83], v[16:31]
	v_mfma_f32_32x32x16_bf16 v[0:15], v[104:107], v[80:83], v[0:15]
	s_cbranch_vccnz .LBB0_1188
	v_pk_add_f32 v[70:71], v[70:71], v[172:173] op_sel_hi:[1,0] neg_lo:[0,1] neg_hi:[0,1]
	v_pk_add_f32 v[78:79], v[78:79], v[172:173] op_sel_hi:[1,0] neg_lo:[0,1] neg_hi:[0,1]
	v_pk_add_f32 v[64:65], v[64:65], v[172:173] op_sel_hi:[1,0] neg_lo:[0,1] neg_hi:[0,1]
	v_pk_add_f32 v[66:67], v[66:67], v[172:173] op_sel_hi:[1,0] neg_lo:[0,1] neg_hi:[0,1]
	v_pk_add_f32 v[68:69], v[68:69], v[172:173] op_sel_hi:[1,0] neg_lo:[0,1] neg_hi:[0,1]
	v_pk_add_f32 v[72:73], v[72:73], v[172:173] op_sel_hi:[1,0] neg_lo:[0,1] neg_hi:[0,1]
	v_pk_add_f32 v[74:75], v[74:75], v[172:173] op_sel_hi:[1,0] neg_lo:[0,1] neg_hi:[0,1]
	v_pk_add_f32 v[76:77], v[76:77], v[172:173] op_sel_hi:[1,0] neg_lo:[0,1] neg_hi:[0,1]
	v_pk_add_f32 v[62:63], v[62:63], v[172:173] op_sel_hi:[1,0] neg_lo:[0,1] neg_hi:[0,1]
	v_max_f32_e32 v82, v70, v71
	v_max_f32_e32 v85, v78, v79
	v_pk_add_f32 v[50:51], v[50:51], v[172:173] op_sel_hi:[1,0] neg_lo:[0,1] neg_hi:[0,1]
	v_pk_add_f32 v[54:55], v[54:55], v[172:173] op_sel_hi:[1,0] neg_lo:[0,1] neg_hi:[0,1]
	v_pk_add_f32 v[56:57], v[56:57], v[172:173] op_sel_hi:[1,0] neg_lo:[0,1] neg_hi:[0,1]
	v_pk_add_f32 v[58:59], v[58:59], v[172:173] op_sel_hi:[1,0] neg_lo:[0,1] neg_hi:[0,1]
	v_pk_add_f32 v[60:61], v[60:61], v[172:173] op_sel_hi:[1,0] neg_lo:[0,1] neg_hi:[0,1]
	v_max_f32_e32 v80, v64, v65
	v_max_f32_e32 v81, v66, v67
	v_max3_f32 v82, v68, v69, v82
	v_max_f32_e32 v83, v72, v73
	v_max_f32_e32 v84, v74, v75
	v_max3_f32 v85, v76, v77, v85
	v_max_f32_e32 v86, v62, v63
	v_pk_add_f32 v[48:49], v[48:49], v[172:173] op_sel_hi:[1,0] neg_lo:[0,1] neg_hi:[0,1]
	v_pk_add_f32 v[52:53], v[52:53], v[172:173] op_sel_hi:[1,0] neg_lo:[0,1] neg_hi:[0,1]
	v_max3_f32 v80, v80, v81, v82
	v_max3_f32 v81, v83, v84, v85
	v_max_f32_e32 v82, v50, v51
	v_max_f32_e32 v83, v54, v55
	v_max_f32_e32 v84, v56, v57
	v_max_f32_e32 v85, v58, v59
	v_max3_f32 v86, v60, v61, v86
	v_max3_f32 v82, v48, v49, v82
	v_max3_f32 v83, v52, v53, v83
	v_max3_f32 v84, v84, v85, v86
	v_max3_f32 v82, v82, v83, v84
	v_max3_f32 v80, v80, v81, v82
	ds_bpermute_b32 v81, v218, v80
	s_mov_b32 s14, 0x41000000
	s_waitcnt lgkmcnt(0)
	v_max_f32_e32 v81, v81, v81
	v_max_f32_e32 v80, v80, v81
	v_cmp_lt_f32_e32 vcc, s14, v80
	s_cbranch_vccz .LBB0_1188
	v_max_f32_e32 v80, v80, v80
	v_max_f32_e32 v81, 0, v80
	v_exp_f32_e64 v80, -v81
	v_sub_f32_e32 v79, v79, v81
	v_sub_f32_e32 v78, v78, v81
	v_sub_f32_e32 v77, v77, v81
	v_sub_f32_e32 v76, v76, v81
	v_sub_f32_e32 v75, v75, v81
	v_sub_f32_e32 v74, v74, v81
	v_sub_f32_e32 v73, v73, v81
	v_sub_f32_e32 v72, v72, v81
	v_sub_f32_e32 v71, v71, v81
	v_sub_f32_e32 v70, v70, v81
	v_sub_f32_e32 v69, v69, v81
	v_sub_f32_e32 v68, v68, v81
	v_sub_f32_e32 v67, v67, v81
	v_sub_f32_e32 v66, v66, v81
	v_sub_f32_e32 v65, v65, v81
	v_sub_f32_e32 v64, v64, v81
	v_sub_f32_e32 v63, v63, v81
	v_sub_f32_e32 v62, v62, v81
	v_sub_f32_e32 v61, v61, v81
	v_sub_f32_e32 v60, v60, v81
	v_sub_f32_e32 v59, v59, v81
	v_sub_f32_e32 v58, v58, v81
	v_sub_f32_e32 v57, v57, v81
	v_sub_f32_e32 v56, v56, v81
	v_sub_f32_e32 v55, v55, v81
	v_sub_f32_e32 v54, v54, v81
	v_sub_f32_e32 v53, v53, v81
	v_sub_f32_e32 v52, v52, v81
	v_sub_f32_e32 v51, v51, v81
	v_sub_f32_e32 v50, v50, v81
	v_sub_f32_e32 v49, v49, v81
	v_sub_f32_e32 v48, v48, v81
	v_pk_mul_f32 v[14:15], v[14:15], v[80:81] op_sel_hi:[1,0]
	v_pk_mul_f32 v[12:13], v[12:13], v[80:81] op_sel_hi:[1,0]
	v_pk_mul_f32 v[10:11], v[10:11], v[80:81] op_sel_hi:[1,0]
	v_pk_mul_f32 v[8:9], v[8:9], v[80:81] op_sel_hi:[1,0]
	v_pk_mul_f32 v[6:7], v[6:7], v[80:81] op_sel_hi:[1,0]
	v_pk_mul_f32 v[4:5], v[4:5], v[80:81] op_sel_hi:[1,0]
	v_pk_mul_f32 v[2:3], v[2:3], v[80:81] op_sel_hi:[1,0]
	v_pk_mul_f32 v[0:1], v[0:1], v[80:81] op_sel_hi:[1,0]
	v_pk_mul_f32 v[30:31], v[30:31], v[80:81] op_sel_hi:[1,0]
	v_pk_mul_f32 v[28:29], v[28:29], v[80:81] op_sel_hi:[1,0]
	v_pk_mul_f32 v[26:27], v[26:27], v[80:81] op_sel_hi:[1,0]
	v_pk_mul_f32 v[24:25], v[24:25], v[80:81] op_sel_hi:[1,0]
	v_pk_mul_f32 v[22:23], v[22:23], v[80:81] op_sel_hi:[1,0]
	v_pk_mul_f32 v[20:21], v[20:21], v[80:81] op_sel_hi:[1,0]
	v_pk_mul_f32 v[18:19], v[18:19], v[80:81] op_sel_hi:[1,0]
	v_pk_mul_f32 v[16:17], v[16:17], v[80:81] op_sel_hi:[1,0]
	v_pk_mul_f32 v[46:47], v[46:47], v[80:81] op_sel_hi:[1,0]
	v_pk_mul_f32 v[44:45], v[44:45], v[80:81] op_sel_hi:[1,0]
	v_pk_mul_f32 v[42:43], v[42:43], v[80:81] op_sel_hi:[1,0]
	v_pk_mul_f32 v[40:41], v[40:41], v[80:81] op_sel_hi:[1,0]
	v_pk_mul_f32 v[38:39], v[38:39], v[80:81] op_sel_hi:[1,0]
	v_pk_mul_f32 v[36:37], v[36:37], v[80:81] op_sel_hi:[1,0]
	v_pk_mul_f32 v[34:35], v[34:35], v[80:81] op_sel_hi:[1,0]
	v_pk_mul_f32 v[32:33], v[32:33], v[80:81] op_sel_hi:[1,0]
	v_add_f32_e32 v172, v172, v81
	s_branch .LBB0_1188

.LBB0_1213:
	s_mov_b32 m0, s12
	v_lshl_add_u64 v[80:81], v[84:85], 0, s[8:9]
	s_mov_b64 s[8:9], 0x1f80
	global_load_lds_dwordx4 v[80:81], off
	v_lshl_add_u64 v[80:81], v[178:179], 0, s[8:9]
	s_mov_b32 m0, s17
	v_exp_f32_e32 v150, v64
	global_load_lds_dwordx4 v[80:81], off
	ds_read_b128 v[80:83], v199 offset:12288
	ds_read_b128 v[84:87], v199 offset:18432
	ds_read_b128 v[154:157], v200 offset:12288
	ds_read_b128 v[176:179], v200 offset:18432
	ds_read_b128 v[180:183], v199 offset:12352
	ds_read_b128 v[184:187], v199 offset:18496
	ds_read_b128 v[188:191], v200 offset:12352
	ds_read_b128 v[202:205], v200 offset:18496
	ds_read_b128 v[212:215], v199 offset:12416
	ds_read_b128 v[220:223], v199 offset:18560
	ds_read_b128 v[224:227], v200 offset:12416
	ds_read_b128 v[228:231], v200 offset:18560
	s_waitcnt lgkmcnt(0)
	v_mfma_f32_32x32x16_bf16 v[96:111], v[80:83], v[136:139], 0
	v_exp_f32_e32 v151, v65
	v_exp_f32_e32 v152, v48
	v_exp_f32_e32 v153, v49
	v_exp_f32_e32 v167, v50
	v_exp_f32_e32 v169, v51
	v_exp_f32_e32 v201, v77
	v_exp_f32_e32 v208, v62
	v_mfma_f32_32x32x16_bf16 v[80:95], v[84:87], v[136:139], 0
	v_exp_f32_e32 v209, v63
	v_mfma_f32_32x32x16_bf16 v[96:111], v[154:157], v[132:135], v[96:111]
	v_exp_f32_e32 v155, v66
	v_exp_f32_e32 v156, v67
	v_exp_f32_e32 v157, v68
	v_mfma_f32_32x32x16_bf16 v[96:111], v[180:183], v[128:131], v[96:111]
	v_exp_f32_e32 v180, v69
	v_exp_f32_e32 v181, v52
	v_exp_f32_e32 v182, v55
	v_exp_f32_e32 v183, v72
	v_mfma_f32_32x32x16_bf16 v[96:111], v[188:191], v[124:127], v[96:111]
	v_exp_f32_e32 v188, v73
	v_exp_f32_e32 v189, v58
	v_exp_f32_e32 v190, v59
	v_exp_f32_e32 v191, v76
	v_mfma_f32_32x32x16_bf16 v[96:111], v[212:215], v[120:123], v[96:111]
	v_mfma_f32_32x32x16_bf16 v[96:111], v[224:227], v[116:119], v[96:111]
	v_mfma_f32_32x32x16_bf16 v[80:95], v[176:179], v[132:135], v[80:95]
	v_exp_f32_e32 v176, v53
	v_exp_f32_e32 v177, v70
	v_exp_f32_e32 v178, v71
	v_exp_f32_e32 v179, v54
	v_mfma_f32_32x32x16_bf16 v[80:95], v[184:187], v[128:131], v[80:95]
	v_exp_f32_e32 v184, v56
	v_exp_f32_e32 v185, v57
	v_exp_f32_e32 v186, v74
	v_exp_f32_e32 v187, v75
	v_mfma_f32_32x32x16_bf16 v[80:95], v[202:205], v[124:127], v[80:95]
	v_exp_f32_e32 v202, v60
	v_exp_f32_e32 v203, v61
	v_exp_f32_e32 v204, v78
	v_exp_f32_e32 v205, v79
	v_mfma_f32_32x32x16_bf16 v[80:95], v[220:223], v[120:123], v[80:95]
	ds_read_b128 v[48:51], v173 offset:49152
	ds_read_b128 v[52:55], v173 offset:53248
	ds_read_b128 v[56:59], v197 offset:49152
	ds_read_b128 v[60:63], v197 offset:53248
	ds_read_b128 v[64:67], v193 offset:49152
	ds_read_b128 v[68:71], v193 offset:53248
	ds_read_b128 v[72:75], v195 offset:49152
	ds_read_b128 v[76:79], v195 offset:53248
	v_add_f32_e32 v32, v32, v150
	v_add_f32_e32 v33, v33, v151
	v_cvt_pk_bf16_f32 v154, v150, v151
	v_add_f32_e32 v34, v34, v155
	v_add_f32_e32 v35, v35, v156
	v_cvt_pk_bf16_f32 v155, v155, v156
	v_add_f32_e32 v32, v32, v157
	v_add_f32_e32 v33, v33, v180
	v_cvt_pk_bf16_f32 v156, v157, v180
	v_add_f32_e32 v34, v34, v177
	v_add_f32_e32 v35, v35, v178
	v_cvt_pk_bf16_f32 v157, v177, v178
	v_mfma_f32_32x32x16_bf16 v[80:95], v[228:231], v[116:119], v[80:95]
	s_and_b64 vcc, exec, s[6:7]
	s_waitcnt lgkmcnt(0)
	v_mfma_f32_32x32x16_bf16 v[16:31], v[52:55], v[154:157], v[16:31]
	v_mfma_f32_32x32x16_bf16 v[0:15], v[48:51], v[154:157], v[0:15]
	v_add_f32_e32 v32, v32, v183
	v_add_f32_e32 v33, v33, v188
	v_cvt_pk_bf16_f32 v48, v183, v188
	v_add_f32_e32 v34, v34, v186
	v_add_f32_e32 v35, v35, v187
	v_cvt_pk_bf16_f32 v49, v186, v187
	v_add_f32_e32 v32, v32, v191
	v_add_f32_e32 v33, v33, v201
	v_cvt_pk_bf16_f32 v50, v191, v201
	v_cvt_pk_bf16_f32 v51, v204, v205
	v_add_f32_e32 v34, v34, v204
	v_add_f32_e32 v35, v35, v205
	v_mfma_f32_32x32x16_bf16 v[16:31], v[60:63], v[48:51], v[16:31]
	v_mfma_f32_32x32x16_bf16 v[0:15], v[56:59], v[48:51], v[0:15]
	v_add_f32_e32 v32, v32, v152
	v_add_f32_e32 v33, v33, v153
	v_cvt_pk_bf16_f32 v52, v152, v153
	v_add_f32_e32 v34, v34, v167
	v_add_f32_e32 v35, v35, v169
	v_cvt_pk_bf16_f32 v53, v167, v169
	v_add_f32_e32 v32, v32, v181
	v_add_f32_e32 v33, v33, v176
	v_cvt_pk_bf16_f32 v54, v181, v176
	v_cvt_pk_bf16_f32 v55, v179, v182
	v_add_f32_e32 v34, v34, v179
	v_add_f32_e32 v35, v35, v182
	v_mfma_f32_32x32x16_bf16 v[16:31], v[68:71], v[52:55], v[16:31]
	v_mfma_f32_32x32x16_bf16 v[0:15], v[64:67], v[52:55], v[0:15]
	v_add_f32_e32 v32, v32, v184
	v_add_f32_e32 v33, v33, v185
	v_cvt_pk_bf16_f32 v48, v184, v185
	v_add_f32_e32 v34, v34, v189
	v_add_f32_e32 v35, v35, v190
	v_cvt_pk_bf16_f32 v49, v189, v190
	v_add_f32_e32 v32, v32, v202
	v_add_f32_e32 v33, v33, v203
	v_cvt_pk_bf16_f32 v50, v202, v203
	v_cvt_pk_bf16_f32 v51, v208, v209
	v_add_f32_e32 v34, v34, v208
	v_add_f32_e32 v35, v35, v209
	v_mfma_f32_32x32x16_bf16 v[16:31], v[76:79], v[48:51], v[16:31]
	v_mfma_f32_32x32x16_bf16 v[0:15], v[72:75], v[48:51], v[0:15]
	s_cbranch_vccnz .LBB0_1216
	v_pk_add_f32 v[102:103], v[102:103], v[172:173] op_sel_hi:[1,0] neg_lo:[0,1] neg_hi:[0,1]
	v_pk_add_f32 v[110:111], v[110:111], v[172:173] op_sel_hi:[1,0] neg_lo:[0,1] neg_hi:[0,1]
	v_pk_add_f32 v[96:97], v[96:97], v[172:173] op_sel_hi:[1,0] neg_lo:[0,1] neg_hi:[0,1]
	v_pk_add_f32 v[98:99], v[98:99], v[172:173] op_sel_hi:[1,0] neg_lo:[0,1] neg_hi:[0,1]
	v_pk_add_f32 v[100:101], v[100:101], v[172:173] op_sel_hi:[1,0] neg_lo:[0,1] neg_hi:[0,1]
	v_pk_add_f32 v[104:105], v[104:105], v[172:173] op_sel_hi:[1,0] neg_lo:[0,1] neg_hi:[0,1]
	v_pk_add_f32 v[106:107], v[106:107], v[172:173] op_sel_hi:[1,0] neg_lo:[0,1] neg_hi:[0,1]
	v_pk_add_f32 v[108:109], v[108:109], v[172:173] op_sel_hi:[1,0] neg_lo:[0,1] neg_hi:[0,1]
	v_pk_add_f32 v[94:95], v[94:95], v[172:173] op_sel_hi:[1,0] neg_lo:[0,1] neg_hi:[0,1]
	v_max_f32_e32 v50, v102, v103
	v_max_f32_e32 v53, v110, v111
	v_pk_add_f32 v[82:83], v[82:83], v[172:173] op_sel_hi:[1,0] neg_lo:[0,1] neg_hi:[0,1]
	v_pk_add_f32 v[86:87], v[86:87], v[172:173] op_sel_hi:[1,0] neg_lo:[0,1] neg_hi:[0,1]
	v_pk_add_f32 v[88:89], v[88:89], v[172:173] op_sel_hi:[1,0] neg_lo:[0,1] neg_hi:[0,1]
	v_pk_add_f32 v[90:91], v[90:91], v[172:173] op_sel_hi:[1,0] neg_lo:[0,1] neg_hi:[0,1]
	v_pk_add_f32 v[92:93], v[92:93], v[172:173] op_sel_hi:[1,0] neg_lo:[0,1] neg_hi:[0,1]
	v_max_f32_e32 v48, v96, v97
	v_max_f32_e32 v49, v98, v99
	v_max3_f32 v50, v100, v101, v50
	v_max_f32_e32 v51, v104, v105
	v_max_f32_e32 v52, v106, v107
	v_max3_f32 v53, v108, v109, v53
	v_max_f32_e32 v54, v94, v95
	v_pk_add_f32 v[80:81], v[80:81], v[172:173] op_sel_hi:[1,0] neg_lo:[0,1] neg_hi:[0,1]
	v_pk_add_f32 v[84:85], v[84:85], v[172:173] op_sel_hi:[1,0] neg_lo:[0,1] neg_hi:[0,1]
	v_max3_f32 v48, v48, v49, v50
	v_max3_f32 v49, v51, v52, v53
	v_max_f32_e32 v50, v82, v83
	v_max_f32_e32 v51, v86, v87
	v_max_f32_e32 v52, v88, v89
	v_max_f32_e32 v53, v90, v91
	v_max3_f32 v54, v92, v93, v54
	v_max3_f32 v50, v80, v81, v50
	v_max3_f32 v51, v84, v85, v51
	v_max3_f32 v52, v52, v53, v54
	v_max3_f32 v50, v50, v51, v52
	v_max3_f32 v48, v48, v49, v50
	ds_bpermute_b32 v49, v218, v48
	s_mov_b32 s8, 0x41000000
	s_waitcnt lgkmcnt(0)
	v_max_f32_e32 v49, v49, v49
	v_max_f32_e32 v48, v48, v49
	v_cmp_lt_f32_e32 vcc, s8, v48
	s_cbranch_vccz .LBB0_1216
	v_max_f32_e32 v48, v48, v48
	v_max_f32_e32 v49, 0, v48
	v_exp_f32_e64 v48, -v49
	v_sub_f32_e32 v96, v96, v49
	v_sub_f32_e32 v97, v97, v49
	v_sub_f32_e32 v98, v98, v49
	v_sub_f32_e32 v99, v99, v49
	v_sub_f32_e32 v100, v100, v49
	v_sub_f32_e32 v101, v101, v49
	v_sub_f32_e32 v102, v102, v49
	v_sub_f32_e32 v103, v103, v49
	v_sub_f32_e32 v104, v104, v49
	v_sub_f32_e32 v105, v105, v49
	v_sub_f32_e32 v106, v106, v49
	v_sub_f32_e32 v107, v107, v49
	v_sub_f32_e32 v108, v108, v49
	v_sub_f32_e32 v109, v109, v49
	v_sub_f32_e32 v110, v110, v49
	v_sub_f32_e32 v111, v111, v49
	v_sub_f32_e32 v80, v80, v49
	v_sub_f32_e32 v81, v81, v49
	v_sub_f32_e32 v82, v82, v49
	v_sub_f32_e32 v83, v83, v49
	v_sub_f32_e32 v84, v84, v49
	v_sub_f32_e32 v85, v85, v49
	v_sub_f32_e32 v86, v86, v49
	v_sub_f32_e32 v87, v87, v49
	v_sub_f32_e32 v88, v88, v49
	v_sub_f32_e32 v89, v89, v49
	v_sub_f32_e32 v90, v90, v49
	v_sub_f32_e32 v91, v91, v49
	v_sub_f32_e32 v92, v92, v49
	v_sub_f32_e32 v93, v93, v49
	v_sub_f32_e32 v94, v94, v49
	v_sub_f32_e32 v95, v95, v49
	v_pk_mul_f32 v[14:15], v[14:15], v[48:49] op_sel_hi:[1,0]
	v_pk_mul_f32 v[12:13], v[12:13], v[48:49] op_sel_hi:[1,0]
	v_pk_mul_f32 v[10:11], v[10:11], v[48:49] op_sel_hi:[1,0]
	v_pk_mul_f32 v[8:9], v[8:9], v[48:49] op_sel_hi:[1,0]
	v_pk_mul_f32 v[6:7], v[6:7], v[48:49] op_sel_hi:[1,0]
	v_pk_mul_f32 v[4:5], v[4:5], v[48:49] op_sel_hi:[1,0]
	v_pk_mul_f32 v[2:3], v[2:3], v[48:49] op_sel_hi:[1,0]
	v_pk_mul_f32 v[0:1], v[0:1], v[48:49] op_sel_hi:[1,0]
	v_pk_mul_f32 v[30:31], v[30:31], v[48:49] op_sel_hi:[1,0]
	v_pk_mul_f32 v[28:29], v[28:29], v[48:49] op_sel_hi:[1,0]
	v_pk_mul_f32 v[26:27], v[26:27], v[48:49] op_sel_hi:[1,0]
	v_pk_mul_f32 v[24:25], v[24:25], v[48:49] op_sel_hi:[1,0]
	v_pk_mul_f32 v[22:23], v[22:23], v[48:49] op_sel_hi:[1,0]
	v_pk_mul_f32 v[20:21], v[20:21], v[48:49] op_sel_hi:[1,0]
	v_pk_mul_f32 v[18:19], v[18:19], v[48:49] op_sel_hi:[1,0]
	v_pk_mul_f32 v[16:17], v[16:17], v[48:49] op_sel_hi:[1,0]
	v_pk_mul_f32 v[46:47], v[46:47], v[48:49] op_sel_hi:[1,0]
	v_pk_mul_f32 v[44:45], v[44:45], v[48:49] op_sel_hi:[1,0]
	v_pk_mul_f32 v[42:43], v[42:43], v[48:49] op_sel_hi:[1,0]
	v_pk_mul_f32 v[40:41], v[40:41], v[48:49] op_sel_hi:[1,0]
	v_pk_mul_f32 v[38:39], v[38:39], v[48:49] op_sel_hi:[1,0]
	v_pk_mul_f32 v[36:37], v[36:37], v[48:49] op_sel_hi:[1,0]
	v_pk_mul_f32 v[34:35], v[34:35], v[48:49] op_sel_hi:[1,0]
	v_pk_mul_f32 v[32:33], v[32:33], v[48:49] op_sel_hi:[1,0]
	v_add_f32_e32 v172, v172, v49
.LBB0_1216:
	ds_read_b128 v[48:51], v199 offset:24576
	ds_read_b128 v[52:55], v199 offset:30720
	ds_read_b128 v[154:157], v200 offset:24576
	ds_read_b128 v[176:179], v200 offset:30720
	ds_read_b128 v[180:183], v199 offset:24640
	ds_read_b128 v[184:187], v199 offset:30784
	ds_read_b128 v[188:191], v200 offset:24640
	ds_read_b128 v[202:205], v200 offset:30784
	ds_read_b128 v[212:215], v199 offset:24704
	ds_read_b128 v[220:223], v199 offset:30848
	ds_read_b128 v[224:227], v200 offset:24704
	ds_read_b128 v[228:231], v200 offset:30848
	s_waitcnt lgkmcnt(0)
	v_mfma_f32_32x32x16_bf16 v[64:79], v[48:51], v[136:139], 0
	v_exp_f32_e32 v150, v96
	v_exp_f32_e32 v151, v97
	v_exp_f32_e32 v152, v80
	v_exp_f32_e32 v153, v81
	v_exp_f32_e32 v167, v82
	v_exp_f32_e32 v169, v83
	v_exp_f32_e32 v201, v109
	v_mfma_f32_32x32x16_bf16 v[48:63], v[52:55], v[136:139], 0
	v_exp_f32_e32 v208, v94
	v_exp_f32_e32 v209, v95
	v_mfma_f32_32x32x16_bf16 v[64:79], v[154:157], v[132:135], v[64:79]
	v_exp_f32_e32 v155, v98
	v_exp_f32_e32 v156, v99
	v_exp_f32_e32 v157, v100
	v_mfma_f32_32x32x16_bf16 v[64:79], v[180:183], v[128:131], v[64:79]
	v_exp_f32_e32 v180, v101
	v_exp_f32_e32 v181, v84
	v_exp_f32_e32 v182, v87
	v_exp_f32_e32 v183, v104
	v_mfma_f32_32x32x16_bf16 v[64:79], v[188:191], v[124:127], v[64:79]
	v_exp_f32_e32 v188, v105
	v_exp_f32_e32 v189, v90
	v_exp_f32_e32 v190, v91
	v_exp_f32_e32 v191, v108
	v_mfma_f32_32x32x16_bf16 v[64:79], v[212:215], v[120:123], v[64:79]
	v_mfma_f32_32x32x16_bf16 v[64:79], v[224:227], v[116:119], v[64:79]
	v_mfma_f32_32x32x16_bf16 v[48:63], v[176:179], v[132:135], v[48:63]
	v_exp_f32_e32 v176, v85
	v_exp_f32_e32 v177, v102
	v_exp_f32_e32 v178, v103
	v_exp_f32_e32 v179, v86
	v_mfma_f32_32x32x16_bf16 v[48:63], v[184:187], v[128:131], v[48:63]
	v_exp_f32_e32 v184, v88
	v_exp_f32_e32 v185, v89
	v_exp_f32_e32 v186, v106
	v_exp_f32_e32 v187, v107
	v_mfma_f32_32x32x16_bf16 v[48:63], v[202:205], v[124:127], v[48:63]
	v_exp_f32_e32 v202, v92
	v_exp_f32_e32 v203, v93
	v_exp_f32_e32 v204, v110
	v_exp_f32_e32 v205, v111
	v_mfma_f32_32x32x16_bf16 v[48:63], v[220:223], v[120:123], v[48:63]
	ds_read_b128 v[80:83], v173 offset:57344
	ds_read_b128 v[84:87], v173 offset:61440
	ds_read_b128 v[88:91], v197 offset:57344
	ds_read_b128 v[92:95], v197 offset:61440
	ds_read_b128 v[96:99], v193 offset:57344
	ds_read_b128 v[100:103], v193 offset:61440
	ds_read_b128 v[104:107], v195 offset:57344
	ds_read_b128 v[108:111], v195 offset:61440
	v_add_f32_e32 v32, v32, v150
	v_add_f32_e32 v33, v33, v151
	v_cvt_pk_bf16_f32 v154, v150, v151
	v_add_f32_e32 v34, v34, v155
	v_add_f32_e32 v35, v35, v156
	v_cvt_pk_bf16_f32 v155, v155, v156
	v_add_f32_e32 v32, v32, v157
	v_add_f32_e32 v33, v33, v180
	v_cvt_pk_bf16_f32 v156, v157, v180
	v_add_f32_e32 v34, v34, v177
	v_add_f32_e32 v35, v35, v178
	v_cvt_pk_bf16_f32 v157, v177, v178
	v_mfma_f32_32x32x16_bf16 v[48:63], v[228:231], v[116:119], v[48:63]
	s_and_b64 vcc, exec, s[6:7]
	s_waitcnt lgkmcnt(0)
	v_mfma_f32_32x32x16_bf16 v[16:31], v[84:87], v[154:157], v[16:31]
	v_mfma_f32_32x32x16_bf16 v[0:15], v[80:83], v[154:157], v[0:15]
	v_add_f32_e32 v32, v32, v183
	v_add_f32_e32 v33, v33, v188
	v_cvt_pk_bf16_f32 v80, v183, v188
	v_add_f32_e32 v34, v34, v186
	v_add_f32_e32 v35, v35, v187
	v_cvt_pk_bf16_f32 v81, v186, v187
	v_add_f32_e32 v32, v32, v191
	v_add_f32_e32 v33, v33, v201
	v_cvt_pk_bf16_f32 v82, v191, v201
	v_cvt_pk_bf16_f32 v83, v204, v205
	v_add_f32_e32 v34, v34, v204
	v_add_f32_e32 v35, v35, v205
	v_mfma_f32_32x32x16_bf16 v[16:31], v[92:95], v[80:83], v[16:31]
	v_mfma_f32_32x32x16_bf16 v[0:15], v[88:91], v[80:83], v[0:15]
	v_add_f32_e32 v32, v32, v152
	v_add_f32_e32 v33, v33, v153
	v_cvt_pk_bf16_f32 v84, v152, v153
	v_add_f32_e32 v34, v34, v167
	v_add_f32_e32 v35, v35, v169
	v_cvt_pk_bf16_f32 v85, v167, v169
	v_add_f32_e32 v32, v32, v181
	v_add_f32_e32 v33, v33, v176
	v_cvt_pk_bf16_f32 v86, v181, v176
	v_cvt_pk_bf16_f32 v87, v179, v182
	v_add_f32_e32 v34, v34, v179
	v_add_f32_e32 v35, v35, v182
	v_mfma_f32_32x32x16_bf16 v[16:31], v[100:103], v[84:87], v[16:31]
	v_mfma_f32_32x32x16_bf16 v[0:15], v[96:99], v[84:87], v[0:15]
	v_add_f32_e32 v32, v32, v184
	v_add_f32_e32 v33, v33, v185
	v_cvt_pk_bf16_f32 v80, v184, v185
	v_add_f32_e32 v34, v34, v189
	v_add_f32_e32 v35, v35, v190
	v_cvt_pk_bf16_f32 v81, v189, v190
	v_add_f32_e32 v32, v32, v202
	v_add_f32_e32 v33, v33, v203
	v_cvt_pk_bf16_f32 v82, v202, v203
	v_cvt_pk_bf16_f32 v83, v208, v209
	v_add_f32_e32 v34, v34, v208
	v_add_f32_e32 v35, v35, v209
	v_mfma_f32_32x32x16_bf16 v[16:31], v[108:111], v[80:83], v[16:31]
	v_mfma_f32_32x32x16_bf16 v[0:15], v[104:107], v[80:83], v[0:15]
	s_cbranch_vccnz .LBB0_1219
	v_pk_add_f32 v[70:71], v[70:71], v[172:173] op_sel_hi:[1,0] neg_lo:[0,1] neg_hi:[0,1]
	v_pk_add_f32 v[78:79], v[78:79], v[172:173] op_sel_hi:[1,0] neg_lo:[0,1] neg_hi:[0,1]
	v_pk_add_f32 v[64:65], v[64:65], v[172:173] op_sel_hi:[1,0] neg_lo:[0,1] neg_hi:[0,1]
	v_pk_add_f32 v[66:67], v[66:67], v[172:173] op_sel_hi:[1,0] neg_lo:[0,1] neg_hi:[0,1]
	v_pk_add_f32 v[68:69], v[68:69], v[172:173] op_sel_hi:[1,0] neg_lo:[0,1] neg_hi:[0,1]
	v_pk_add_f32 v[72:73], v[72:73], v[172:173] op_sel_hi:[1,0] neg_lo:[0,1] neg_hi:[0,1]
	v_pk_add_f32 v[74:75], v[74:75], v[172:173] op_sel_hi:[1,0] neg_lo:[0,1] neg_hi:[0,1]
	v_pk_add_f32 v[76:77], v[76:77], v[172:173] op_sel_hi:[1,0] neg_lo:[0,1] neg_hi:[0,1]
	v_pk_add_f32 v[62:63], v[62:63], v[172:173] op_sel_hi:[1,0] neg_lo:[0,1] neg_hi:[0,1]
	v_max_f32_e32 v82, v70, v71
	v_max_f32_e32 v85, v78, v79
	v_pk_add_f32 v[50:51], v[50:51], v[172:173] op_sel_hi:[1,0] neg_lo:[0,1] neg_hi:[0,1]
	v_pk_add_f32 v[54:55], v[54:55], v[172:173] op_sel_hi:[1,0] neg_lo:[0,1] neg_hi:[0,1]
	v_pk_add_f32 v[56:57], v[56:57], v[172:173] op_sel_hi:[1,0] neg_lo:[0,1] neg_hi:[0,1]
	v_pk_add_f32 v[58:59], v[58:59], v[172:173] op_sel_hi:[1,0] neg_lo:[0,1] neg_hi:[0,1]
	v_pk_add_f32 v[60:61], v[60:61], v[172:173] op_sel_hi:[1,0] neg_lo:[0,1] neg_hi:[0,1]
	v_max_f32_e32 v80, v64, v65
	v_max_f32_e32 v81, v66, v67
	v_max3_f32 v82, v68, v69, v82
	v_max_f32_e32 v83, v72, v73
	v_max_f32_e32 v84, v74, v75
	v_max3_f32 v85, v76, v77, v85
	v_max_f32_e32 v86, v62, v63
	v_pk_add_f32 v[48:49], v[48:49], v[172:173] op_sel_hi:[1,0] neg_lo:[0,1] neg_hi:[0,1]
	v_pk_add_f32 v[52:53], v[52:53], v[172:173] op_sel_hi:[1,0] neg_lo:[0,1] neg_hi:[0,1]
	v_max3_f32 v80, v80, v81, v82
	v_max3_f32 v81, v83, v84, v85
	v_max_f32_e32 v82, v50, v51
	v_max_f32_e32 v83, v54, v55
	v_max_f32_e32 v84, v56, v57
	v_max_f32_e32 v85, v58, v59
	v_max3_f32 v86, v60, v61, v86
	v_max3_f32 v82, v48, v49, v82
	v_max3_f32 v83, v52, v53, v83
	v_max3_f32 v84, v84, v85, v86
	v_max3_f32 v82, v82, v83, v84
	v_max3_f32 v80, v80, v81, v82
	ds_bpermute_b32 v81, v218, v80
	s_mov_b32 s8, 0x41000000
	s_waitcnt lgkmcnt(0)
	v_max_f32_e32 v81, v81, v81
	v_max_f32_e32 v80, v80, v81
	v_cmp_lt_f32_e32 vcc, s8, v80
	s_cbranch_vccz .LBB0_1219
	v_max_f32_e32 v80, v80, v80
	v_max_f32_e32 v81, 0, v80
	v_exp_f32_e64 v80, -v81
	v_sub_f32_e32 v64, v64, v81
	v_sub_f32_e32 v65, v65, v81
	v_sub_f32_e32 v66, v66, v81
	v_sub_f32_e32 v67, v67, v81
	v_sub_f32_e32 v68, v68, v81
	v_sub_f32_e32 v69, v69, v81
	v_sub_f32_e32 v70, v70, v81
	v_sub_f32_e32 v71, v71, v81
	v_sub_f32_e32 v72, v72, v81
	v_sub_f32_e32 v73, v73, v81
	v_sub_f32_e32 v74, v74, v81
	v_sub_f32_e32 v75, v75, v81
	v_sub_f32_e32 v76, v76, v81
	v_sub_f32_e32 v77, v77, v81
	v_sub_f32_e32 v78, v78, v81
	v_sub_f32_e32 v79, v79, v81
	v_sub_f32_e32 v48, v48, v81
	v_sub_f32_e32 v49, v49, v81
	v_sub_f32_e32 v50, v50, v81
	v_sub_f32_e32 v51, v51, v81
	v_sub_f32_e32 v52, v52, v81
	v_sub_f32_e32 v53, v53, v81
	v_sub_f32_e32 v54, v54, v81
	v_sub_f32_e32 v55, v55, v81
	v_sub_f32_e32 v56, v56, v81
	v_sub_f32_e32 v57, v57, v81
	v_sub_f32_e32 v58, v58, v81
	v_sub_f32_e32 v59, v59, v81
	v_sub_f32_e32 v60, v60, v81
	v_sub_f32_e32 v61, v61, v81
	v_sub_f32_e32 v62, v62, v81
	v_sub_f32_e32 v63, v63, v81
	v_pk_mul_f32 v[14:15], v[14:15], v[80:81] op_sel_hi:[1,0]
	v_pk_mul_f32 v[12:13], v[12:13], v[80:81] op_sel_hi:[1,0]
	v_pk_mul_f32 v[10:11], v[10:11], v[80:81] op_sel_hi:[1,0]
	v_pk_mul_f32 v[8:9], v[8:9], v[80:81] op_sel_hi:[1,0]
	v_pk_mul_f32 v[6:7], v[6:7], v[80:81] op_sel_hi:[1,0]
	v_pk_mul_f32 v[4:5], v[4:5], v[80:81] op_sel_hi:[1,0]
	v_pk_mul_f32 v[2:3], v[2:3], v[80:81] op_sel_hi:[1,0]
	v_pk_mul_f32 v[0:1], v[0:1], v[80:81] op_sel_hi:[1,0]
	v_pk_mul_f32 v[30:31], v[30:31], v[80:81] op_sel_hi:[1,0]
	v_pk_mul_f32 v[28:29], v[28:29], v[80:81] op_sel_hi:[1,0]
	v_pk_mul_f32 v[26:27], v[26:27], v[80:81] op_sel_hi:[1,0]
	v_pk_mul_f32 v[24:25], v[24:25], v[80:81] op_sel_hi:[1,0]
	v_pk_mul_f32 v[22:23], v[22:23], v[80:81] op_sel_hi:[1,0]
	v_pk_mul_f32 v[20:21], v[20:21], v[80:81] op_sel_hi:[1,0]
	v_pk_mul_f32 v[18:19], v[18:19], v[80:81] op_sel_hi:[1,0]
	v_pk_mul_f32 v[16:17], v[16:17], v[80:81] op_sel_hi:[1,0]
	v_pk_mul_f32 v[46:47], v[46:47], v[80:81] op_sel_hi:[1,0]
	v_pk_mul_f32 v[44:45], v[44:45], v[80:81] op_sel_hi:[1,0]
	v_pk_mul_f32 v[42:43], v[42:43], v[80:81] op_sel_hi:[1,0]
	v_pk_mul_f32 v[40:41], v[40:41], v[80:81] op_sel_hi:[1,0]
	v_pk_mul_f32 v[38:39], v[38:39], v[80:81] op_sel_hi:[1,0]
	v_pk_mul_f32 v[36:37], v[36:37], v[80:81] op_sel_hi:[1,0]
	v_pk_mul_f32 v[34:35], v[34:35], v[80:81] op_sel_hi:[1,0]
	v_pk_mul_f32 v[32:33], v[32:33], v[80:81] op_sel_hi:[1,0]
	v_add_f32_e32 v172, v172, v81
.LBB0_1219:
	v_lshlrev_b64 v[80:81], 7, v[174:175]
	v_lshl_add_u64 v[80:81], v[144:145], 0, v[80:81]
	s_waitcnt vmcnt(0)
	s_waitcnt vmcnt(0)
	s_barrier
	s_mov_b32 m0, s60
	v_exp_f32_e32 v150, v64
	global_load_lds_dwordx4 v[80:81], off
	ds_read_b128 v[80:83], v199 offset:36864
	ds_read_b128 v[84:87], v199 offset:43008
	ds_read_b128 v[154:157], v200 offset:36864
	ds_read_b128 v[174:177], v200 offset:43008
	ds_read_b128 v[178:181], v199 offset:36928
	ds_read_b128 v[182:185], v199 offset:43072
	ds_read_b128 v[186:189], v200 offset:36928
	ds_read_b128 v[202:205], v200 offset:43072
	ds_read_b128 v[212:215], v199 offset:36992
	ds_read_b128 v[220:223], v199 offset:43136
	ds_read_b128 v[224:227], v200 offset:36992
	ds_read_b128 v[228:231], v200 offset:43136
	s_waitcnt lgkmcnt(0)
	v_mfma_f32_32x32x16_bf16 v[96:111], v[80:83], v[136:139], 0
	v_exp_f32_e32 v151, v65
	v_exp_f32_e32 v152, v48
	v_exp_f32_e32 v153, v49
	v_exp_f32_e32 v167, v50
	v_exp_f32_e32 v169, v51
	v_exp_f32_e32 v190, v77
	v_exp_f32_e32 v191, v60
	v_mfma_f32_32x32x16_bf16 v[80:95], v[84:87], v[136:139], 0
	v_exp_f32_e32 v201, v61
	v_mfma_f32_32x32x16_bf16 v[96:111], v[154:157], v[132:135], v[96:111]
	v_exp_f32_e32 v155, v66
	v_exp_f32_e32 v156, v67
	v_exp_f32_e32 v157, v68
	v_mfma_f32_32x32x16_bf16 v[96:111], v[178:181], v[128:131], v[96:111]
	v_exp_f32_e32 v178, v69
	v_exp_f32_e32 v179, v52
	v_exp_f32_e32 v180, v55
	v_exp_f32_e32 v181, v72
	v_mfma_f32_32x32x16_bf16 v[96:111], v[186:189], v[124:127], v[96:111]
	v_exp_f32_e32 v186, v73
	v_exp_f32_e32 v187, v58
	v_exp_f32_e32 v188, v59
	v_exp_f32_e32 v189, v76
	v_mfma_f32_32x32x16_bf16 v[96:111], v[212:215], v[120:123], v[96:111]
	v_mfma_f32_32x32x16_bf16 v[96:111], v[224:227], v[116:119], v[96:111]
	v_mfma_f32_32x32x16_bf16 v[80:95], v[174:177], v[132:135], v[80:95]
	v_exp_f32_e32 v174, v53
	v_exp_f32_e32 v175, v70
	v_exp_f32_e32 v176, v71
	v_exp_f32_e32 v177, v54
	v_mfma_f32_32x32x16_bf16 v[80:95], v[182:185], v[128:131], v[80:95]
	v_exp_f32_e32 v182, v56
	v_exp_f32_e32 v183, v57
	v_exp_f32_e32 v184, v74
	v_exp_f32_e32 v185, v75
	v_mfma_f32_32x32x16_bf16 v[80:95], v[202:205], v[124:127], v[80:95]
	v_exp_f32_e32 v202, v78
	v_exp_f32_e32 v203, v79
	v_exp_f32_e32 v204, v62
	v_exp_f32_e32 v205, v63
	v_mfma_f32_32x32x16_bf16 v[80:95], v[220:223], v[120:123], v[80:95]
	ds_read_b128 v[48:51], v192 offset:16384
	ds_read_b128 v[52:55], v192 offset:20480
	ds_read_b128 v[56:59], v198 offset:16384
	ds_read_b128 v[60:63], v198 offset:20480
	ds_read_b128 v[64:67], v194 offset:16384
	ds_read_b128 v[68:71], v194 offset:20480
	ds_read_b128 v[72:75], v196 offset:16384
	ds_read_b128 v[76:79], v196 offset:20480
	v_add_f32_e32 v32, v32, v150
	v_add_f32_e32 v33, v33, v151
	v_cvt_pk_bf16_f32 v154, v150, v151
	v_add_f32_e32 v34, v34, v155
	v_add_f32_e32 v35, v35, v156
	v_cvt_pk_bf16_f32 v155, v155, v156
	v_add_f32_e32 v32, v32, v157
	v_add_f32_e32 v33, v33, v178
	v_cvt_pk_bf16_f32 v156, v157, v178
	v_add_f32_e32 v34, v34, v175
	v_add_f32_e32 v35, v35, v176
	v_cvt_pk_bf16_f32 v157, v175, v176
	v_mfma_f32_32x32x16_bf16 v[80:95], v[228:231], v[116:119], v[80:95]
	s_and_b64 vcc, exec, s[6:7]
	s_waitcnt lgkmcnt(0)
	v_mfma_f32_32x32x16_bf16 v[16:31], v[52:55], v[154:157], v[16:31]
	v_mfma_f32_32x32x16_bf16 v[0:15], v[48:51], v[154:157], v[0:15]
	v_add_f32_e32 v32, v32, v181
	v_add_f32_e32 v33, v33, v186
	v_cvt_pk_bf16_f32 v48, v181, v186
	v_add_f32_e32 v34, v34, v184
	v_add_f32_e32 v35, v35, v185
	v_cvt_pk_bf16_f32 v49, v184, v185
	v_add_f32_e32 v32, v32, v189
	v_add_f32_e32 v33, v33, v190
	v_cvt_pk_bf16_f32 v50, v189, v190
	v_cvt_pk_bf16_f32 v51, v202, v203
	v_add_f32_e32 v34, v34, v202
	v_add_f32_e32 v35, v35, v203
	v_mfma_f32_32x32x16_bf16 v[16:31], v[60:63], v[48:51], v[16:31]
	v_mfma_f32_32x32x16_bf16 v[0:15], v[56:59], v[48:51], v[0:15]
	v_add_f32_e32 v32, v32, v152
	v_add_f32_e32 v33, v33, v153
	v_cvt_pk_bf16_f32 v52, v152, v153
	v_add_f32_e32 v34, v34, v167
	v_add_f32_e32 v35, v35, v169
	v_cvt_pk_bf16_f32 v53, v167, v169
	v_add_f32_e32 v32, v32, v179
	v_add_f32_e32 v33, v33, v174
	v_cvt_pk_bf16_f32 v54, v179, v174
	v_cvt_pk_bf16_f32 v55, v177, v180
	v_add_f32_e32 v34, v34, v177
	v_add_f32_e32 v35, v35, v180
	v_mfma_f32_32x32x16_bf16 v[16:31], v[68:71], v[52:55], v[16:31]
	v_mfma_f32_32x32x16_bf16 v[0:15], v[64:67], v[52:55], v[0:15]
	v_add_f32_e32 v32, v32, v182
	v_add_f32_e32 v33, v33, v183
	v_cvt_pk_bf16_f32 v48, v182, v183
	v_add_f32_e32 v34, v34, v187
	v_add_f32_e32 v35, v35, v188
	v_cvt_pk_bf16_f32 v49, v187, v188
	v_add_f32_e32 v32, v32, v191
	v_add_f32_e32 v33, v33, v201
	v_cvt_pk_bf16_f32 v50, v191, v201
	v_cvt_pk_bf16_f32 v51, v204, v205
	v_add_f32_e32 v34, v34, v204
	v_add_f32_e32 v35, v35, v205
	v_mfma_f32_32x32x16_bf16 v[16:31], v[76:79], v[48:51], v[16:31]
	v_mfma_f32_32x32x16_bf16 v[0:15], v[72:75], v[48:51], v[0:15]
	s_cbranch_vccnz .LBB0_1222
	v_pk_add_f32 v[102:103], v[102:103], v[172:173] op_sel_hi:[1,0] neg_lo:[0,1] neg_hi:[0,1]
	v_pk_add_f32 v[110:111], v[110:111], v[172:173] op_sel_hi:[1,0] neg_lo:[0,1] neg_hi:[0,1]
	v_pk_add_f32 v[96:97], v[96:97], v[172:173] op_sel_hi:[1,0] neg_lo:[0,1] neg_hi:[0,1]
	v_pk_add_f32 v[98:99], v[98:99], v[172:173] op_sel_hi:[1,0] neg_lo:[0,1] neg_hi:[0,1]
	v_pk_add_f32 v[100:101], v[100:101], v[172:173] op_sel_hi:[1,0] neg_lo:[0,1] neg_hi:[0,1]
	v_pk_add_f32 v[104:105], v[104:105], v[172:173] op_sel_hi:[1,0] neg_lo:[0,1] neg_hi:[0,1]
	v_pk_add_f32 v[106:107], v[106:107], v[172:173] op_sel_hi:[1,0] neg_lo:[0,1] neg_hi:[0,1]
	v_pk_add_f32 v[108:109], v[108:109], v[172:173] op_sel_hi:[1,0] neg_lo:[0,1] neg_hi:[0,1]
	v_pk_add_f32 v[94:95], v[94:95], v[172:173] op_sel_hi:[1,0] neg_lo:[0,1] neg_hi:[0,1]
	v_max_f32_e32 v50, v102, v103
	v_max_f32_e32 v53, v110, v111
	v_pk_add_f32 v[82:83], v[82:83], v[172:173] op_sel_hi:[1,0] neg_lo:[0,1] neg_hi:[0,1]
	v_pk_add_f32 v[86:87], v[86:87], v[172:173] op_sel_hi:[1,0] neg_lo:[0,1] neg_hi:[0,1]
	v_pk_add_f32 v[88:89], v[88:89], v[172:173] op_sel_hi:[1,0] neg_lo:[0,1] neg_hi:[0,1]
	v_pk_add_f32 v[90:91], v[90:91], v[172:173] op_sel_hi:[1,0] neg_lo:[0,1] neg_hi:[0,1]
	v_pk_add_f32 v[92:93], v[92:93], v[172:173] op_sel_hi:[1,0] neg_lo:[0,1] neg_hi:[0,1]
	v_max_f32_e32 v48, v96, v97
	v_max_f32_e32 v49, v98, v99
	v_max3_f32 v50, v100, v101, v50
	v_max_f32_e32 v51, v104, v105
	v_max_f32_e32 v52, v106, v107
	v_max3_f32 v53, v108, v109, v53
	v_max_f32_e32 v54, v94, v95
	v_pk_add_f32 v[80:81], v[80:81], v[172:173] op_sel_hi:[1,0] neg_lo:[0,1] neg_hi:[0,1]
	v_pk_add_f32 v[84:85], v[84:85], v[172:173] op_sel_hi:[1,0] neg_lo:[0,1] neg_hi:[0,1]
	v_max3_f32 v48, v48, v49, v50
	v_max3_f32 v49, v51, v52, v53
	v_max_f32_e32 v50, v82, v83
	v_max_f32_e32 v51, v86, v87
	v_max_f32_e32 v52, v88, v89
	v_max_f32_e32 v53, v90, v91
	v_max3_f32 v54, v92, v93, v54
	v_max3_f32 v50, v80, v81, v50
	v_max3_f32 v51, v84, v85, v51
	v_max3_f32 v52, v52, v53, v54
	v_max3_f32 v50, v50, v51, v52
	v_max3_f32 v48, v48, v49, v50
	ds_bpermute_b32 v49, v218, v48
	s_mov_b32 s8, 0x41000000
	s_waitcnt lgkmcnt(0)
	v_max_f32_e32 v49, v49, v49
	v_max_f32_e32 v48, v48, v49
	v_cmp_lt_f32_e32 vcc, s8, v48
	s_cbranch_vccz .LBB0_1222
	v_max_f32_e32 v48, v48, v48
	v_max_f32_e32 v49, 0, v48
	v_exp_f32_e64 v48, -v49
	v_sub_f32_e32 v96, v96, v49
	v_sub_f32_e32 v97, v97, v49
	v_sub_f32_e32 v98, v98, v49
	v_sub_f32_e32 v99, v99, v49
	v_sub_f32_e32 v100, v100, v49
	v_sub_f32_e32 v101, v101, v49
	v_sub_f32_e32 v102, v102, v49
	v_sub_f32_e32 v103, v103, v49
	v_sub_f32_e32 v104, v104, v49
	v_sub_f32_e32 v105, v105, v49
	v_sub_f32_e32 v106, v106, v49
	v_sub_f32_e32 v107, v107, v49
	v_sub_f32_e32 v108, v108, v49
	v_sub_f32_e32 v109, v109, v49
	v_sub_f32_e32 v110, v110, v49
	v_sub_f32_e32 v111, v111, v49
	v_sub_f32_e32 v80, v80, v49
	v_sub_f32_e32 v81, v81, v49
	v_sub_f32_e32 v82, v82, v49
	v_sub_f32_e32 v83, v83, v49
	v_sub_f32_e32 v84, v84, v49
	v_sub_f32_e32 v85, v85, v49
	v_sub_f32_e32 v86, v86, v49
	v_sub_f32_e32 v87, v87, v49
	v_sub_f32_e32 v88, v88, v49
	v_sub_f32_e32 v89, v89, v49
	v_sub_f32_e32 v90, v90, v49
	v_sub_f32_e32 v91, v91, v49
	v_sub_f32_e32 v92, v92, v49
	v_sub_f32_e32 v93, v93, v49
	v_sub_f32_e32 v94, v94, v49
	v_sub_f32_e32 v95, v95, v49
	v_pk_mul_f32 v[14:15], v[14:15], v[48:49] op_sel_hi:[1,0]
	v_pk_mul_f32 v[12:13], v[12:13], v[48:49] op_sel_hi:[1,0]
	v_pk_mul_f32 v[10:11], v[10:11], v[48:49] op_sel_hi:[1,0]
	v_pk_mul_f32 v[8:9], v[8:9], v[48:49] op_sel_hi:[1,0]
	v_pk_mul_f32 v[6:7], v[6:7], v[48:49] op_sel_hi:[1,0]
	v_pk_mul_f32 v[4:5], v[4:5], v[48:49] op_sel_hi:[1,0]
	v_pk_mul_f32 v[2:3], v[2:3], v[48:49] op_sel_hi:[1,0]
	v_pk_mul_f32 v[0:1], v[0:1], v[48:49] op_sel_hi:[1,0]
	v_pk_mul_f32 v[30:31], v[30:31], v[48:49] op_sel_hi:[1,0]
	v_pk_mul_f32 v[28:29], v[28:29], v[48:49] op_sel_hi:[1,0]
	v_pk_mul_f32 v[26:27], v[26:27], v[48:49] op_sel_hi:[1,0]
	v_pk_mul_f32 v[24:25], v[24:25], v[48:49] op_sel_hi:[1,0]
	v_pk_mul_f32 v[22:23], v[22:23], v[48:49] op_sel_hi:[1,0]
	v_pk_mul_f32 v[20:21], v[20:21], v[48:49] op_sel_hi:[1,0]
	v_pk_mul_f32 v[18:19], v[18:19], v[48:49] op_sel_hi:[1,0]
	v_pk_mul_f32 v[16:17], v[16:17], v[48:49] op_sel_hi:[1,0]
	v_pk_mul_f32 v[46:47], v[46:47], v[48:49] op_sel_hi:[1,0]
	v_pk_mul_f32 v[44:45], v[44:45], v[48:49] op_sel_hi:[1,0]
	v_pk_mul_f32 v[42:43], v[42:43], v[48:49] op_sel_hi:[1,0]
	v_pk_mul_f32 v[40:41], v[40:41], v[48:49] op_sel_hi:[1,0]
	v_pk_mul_f32 v[38:39], v[38:39], v[48:49] op_sel_hi:[1,0]
	v_pk_mul_f32 v[36:37], v[36:37], v[48:49] op_sel_hi:[1,0]
	v_pk_mul_f32 v[34:35], v[34:35], v[48:49] op_sel_hi:[1,0]
	v_pk_mul_f32 v[32:33], v[32:33], v[48:49] op_sel_hi:[1,0]
	v_add_f32_e32 v172, v172, v49
.LBB0_1222:
	ds_read_b128 v[48:51], v199
	ds_read_b128 v[64:67], v200
	ds_read_b128 v[68:71], v199 offset:64
	ds_read_b128 v[72:75], v200 offset:64
	ds_read_b128 v[76:79], v199 offset:128
	ds_read_b128 v[154:157], v200 offset:128
	v_exp_f32_e32 v96, v96
	v_exp_f32_e32 v97, v97
	v_exp_f32_e32 v98, v98
	s_waitcnt lgkmcnt(0)
	v_mfma_f32_32x32x16_bf16 v[48:63], v[48:51], v[136:139], 0
	v_exp_f32_e32 v136, v80
	v_exp_f32_e32 v137, v81
	v_exp_f32_e32 v99, v99
	v_exp_f32_e32 v100, v100
	v_exp_f32_e32 v101, v101
	v_exp_f32_e32 v102, v102
	v_exp_f32_e32 v103, v103
	v_mfma_f32_32x32x16_bf16 v[48:63], v[64:67], v[132:135], v[48:63]
	v_exp_f32_e32 v132, v82
	v_exp_f32_e32 v133, v83
	v_exp_f32_e32 v134, v84
	v_exp_f32_e32 v104, v104
	v_exp_f32_e32 v105, v105
	v_exp_f32_e32 v106, v106
	v_exp_f32_e32 v107, v107
	v_mfma_f32_32x32x16_bf16 v[48:63], v[68:71], v[128:131], v[48:63]
	v_exp_f32_e32 v128, v85
	v_exp_f32_e32 v129, v86
	v_exp_f32_e32 v130, v87
	v_exp_f32_e32 v108, v108
	v_exp_f32_e32 v109, v109
	v_exp_f32_e32 v92, v92
	v_exp_f32_e32 v93, v93
	v_mfma_f32_32x32x16_bf16 v[48:63], v[72:75], v[124:127], v[48:63]
	v_exp_f32_e32 v124, v88
	v_exp_f32_e32 v125, v89
	v_exp_f32_e32 v126, v90
	v_exp_f32_e32 v127, v91
	v_exp_f32_e32 v110, v110
	v_exp_f32_e32 v111, v111
	v_exp_f32_e32 v94, v94
	v_mfma_f32_32x32x16_bf16 v[48:63], v[76:79], v[120:123], v[48:63]
	v_exp_f32_e32 v95, v95
	v_mfma_f32_32x32x16_bf16 v[48:63], v[154:157], v[116:119], v[48:63]
	s_nop 11
	ds_read_b128 v[56:59], v192 offset:24576
	ds_read_b128 v[60:63], v192 offset:28672
	ds_read_b128 v[64:67], v198 offset:24576
	ds_read_b128 v[68:71], v198 offset:28672
	ds_read_b128 v[72:75], v194 offset:24576
	ds_read_b128 v[76:79], v194 offset:28672
	ds_read_b128 v[80:83], v196 offset:24576
	ds_read_b128 v[84:87], v196 offset:28672
	v_add_f32_e32 v32, v32, v96
	v_add_f32_e32 v33, v33, v97
	v_cvt_pk_bf16_f32 v88, v96, v97
	v_add_f32_e32 v34, v34, v98
	v_add_f32_e32 v35, v35, v99
	v_cvt_pk_bf16_f32 v89, v98, v99
	v_add_f32_e32 v32, v32, v100
	v_add_f32_e32 v33, v33, v101
	v_cvt_pk_bf16_f32 v90, v100, v101
	v_add_f32_e32 v34, v34, v102
	v_add_f32_e32 v35, v35, v103
	v_cvt_pk_bf16_f32 v91, v102, v103
	s_and_b64 vcc, exec, s[6:7]
	s_waitcnt lgkmcnt(0)
	v_mfma_f32_32x32x16_bf16 v[16:31], v[60:63], v[88:91], v[16:31]
	v_mfma_f32_32x32x16_bf16 v[0:15], v[56:59], v[88:91], v[0:15]
	v_add_f32_e32 v32, v32, v104
	v_add_f32_e32 v33, v33, v105
	v_cvt_pk_bf16_f32 v56, v104, v105
	v_add_f32_e32 v34, v34, v106
	v_add_f32_e32 v35, v35, v107
	v_cvt_pk_bf16_f32 v57, v106, v107
	v_add_f32_e32 v32, v32, v108
	v_add_f32_e32 v33, v33, v109
	v_cvt_pk_bf16_f32 v58, v108, v109
	v_add_f32_e32 v34, v34, v110
	v_add_f32_e32 v35, v35, v111
	v_cvt_pk_bf16_f32 v59, v110, v111
	s_nop 1
	v_mfma_f32_32x32x16_bf16 v[16:31], v[68:71], v[56:59], v[16:31]
	v_mfma_f32_32x32x16_bf16 v[0:15], v[64:67], v[56:59], v[0:15]
	v_add_f32_e32 v32, v32, v136
	v_add_f32_e32 v33, v33, v137
	v_cvt_pk_bf16_f32 v56, v136, v137
	v_add_f32_e32 v34, v34, v132
	v_add_f32_e32 v35, v35, v133
	v_cvt_pk_bf16_f32 v57, v132, v133
	v_add_f32_e32 v32, v32, v134
	v_add_f32_e32 v33, v33, v128
	v_cvt_pk_bf16_f32 v58, v134, v128
	v_add_f32_e32 v34, v34, v129
	v_add_f32_e32 v35, v35, v130
	v_cvt_pk_bf16_f32 v59, v129, v130
	s_nop 1
	v_mfma_f32_32x32x16_bf16 v[16:31], v[76:79], v[56:59], v[16:31]
	v_mfma_f32_32x32x16_bf16 v[0:15], v[72:75], v[56:59], v[0:15]
	v_add_f32_e32 v32, v32, v124
	v_add_f32_e32 v33, v33, v125
	v_cvt_pk_bf16_f32 v56, v124, v125
	v_add_f32_e32 v34, v34, v126
	v_add_f32_e32 v35, v35, v127
	v_cvt_pk_bf16_f32 v57, v126, v127
	v_add_f32_e32 v32, v32, v92
	v_add_f32_e32 v33, v33, v93
	v_cvt_pk_bf16_f32 v58, v92, v93
	v_add_f32_e32 v34, v34, v94
	v_add_f32_e32 v35, v35, v95
	v_cvt_pk_bf16_f32 v59, v94, v95
	s_nop 1
	v_mfma_f32_32x32x16_bf16 v[16:31], v[84:87], v[56:59], v[16:31]
	v_mfma_f32_32x32x16_bf16 v[0:15], v[80:83], v[56:59], v[0:15]
	s_cbranch_vccnz .LBB0_1176
	v_pk_add_f32 v[50:51], v[50:51], v[172:173] op_sel_hi:[1,0] neg_lo:[0,1] neg_hi:[0,1]
	v_pk_add_f32 v[54:55], v[54:55], v[172:173] op_sel_hi:[1,0] neg_lo:[0,1] neg_hi:[0,1]
	v_pk_add_f32 v[48:49], v[48:49], v[172:173] op_sel_hi:[1,0] neg_lo:[0,1] neg_hi:[0,1]
	v_pk_add_f32 v[52:53], v[52:53], v[172:173] op_sel_hi:[1,0] neg_lo:[0,1] neg_hi:[0,1]
	v_max_f32_e32 v57, v50, v51
	v_max_f32_e32 v58, v54, v55
	v_sub_f32_e32 v56, 0xff800000, v172
	v_max3_f32 v57, v48, v49, v57
	v_max3_f32 v58, v52, v53, v58
	v_max3_f32 v57, v57, v58, v56
	ds_bpermute_b32 v58, v218, v57
	s_mov_b32 s6, 0x41000000
	s_waitcnt lgkmcnt(0)
	v_max_f32_e32 v58, v58, v58
	v_max_f32_e32 v57, v57, v58
	v_cmp_lt_f32_e32 vcc, s6, v57
	s_cbranch_vccz .LBB0_1177
	v_max_f32_e32 v57, v57, v57
	v_max_f32_e32 v58, 0, v57
	v_exp_f32_e64 v60, -v58
	v_sub_f32_e32 v56, v56, v58
	v_pk_add_f32 v[48:49], v[48:49], v[58:59] op_sel_hi:[1,0] neg_lo:[0,1] neg_hi:[0,1]
	v_pk_add_f32 v[50:51], v[50:51], v[58:59] op_sel_hi:[1,0] neg_lo:[0,1] neg_hi:[0,1]
	v_pk_add_f32 v[52:53], v[52:53], v[58:59] op_sel_hi:[1,0] neg_lo:[0,1] neg_hi:[0,1]
	v_pk_add_f32 v[54:55], v[54:55], v[58:59] op_sel_hi:[1,0] neg_lo:[0,1] neg_hi:[0,1]
	v_pk_mul_f32 v[14:15], v[14:15], v[60:61] op_sel_hi:[1,0]
	v_pk_mul_f32 v[12:13], v[12:13], v[60:61] op_sel_hi:[1,0]
	v_pk_mul_f32 v[10:11], v[10:11], v[60:61] op_sel_hi:[1,0]
	v_pk_mul_f32 v[8:9], v[8:9], v[60:61] op_sel_hi:[1,0]
	v_pk_mul_f32 v[6:7], v[6:7], v[60:61] op_sel_hi:[1,0]
	v_pk_mul_f32 v[4:5], v[4:5], v[60:61] op_sel_hi:[1,0]
	v_pk_mul_f32 v[2:3], v[2:3], v[60:61] op_sel_hi:[1,0]
	v_pk_mul_f32 v[0:1], v[0:1], v[60:61] op_sel_hi:[1,0]
	v_pk_mul_f32 v[30:31], v[30:31], v[60:61] op_sel_hi:[1,0]
	v_pk_mul_f32 v[28:29], v[28:29], v[60:61] op_sel_hi:[1,0]
	v_pk_mul_f32 v[26:27], v[26:27], v[60:61] op_sel_hi:[1,0]
	v_pk_mul_f32 v[24:25], v[24:25], v[60:61] op_sel_hi:[1,0]
	v_pk_mul_f32 v[22:23], v[22:23], v[60:61] op_sel_hi:[1,0]
	v_pk_mul_f32 v[20:21], v[20:21], v[60:61] op_sel_hi:[1,0]
	v_pk_mul_f32 v[18:19], v[18:19], v[60:61] op_sel_hi:[1,0]
	v_pk_mul_f32 v[16:17], v[16:17], v[60:61] op_sel_hi:[1,0]
	v_pk_mul_f32 v[46:47], v[46:47], v[60:61] op_sel_hi:[1,0]
	v_pk_mul_f32 v[44:45], v[44:45], v[60:61] op_sel_hi:[1,0]
	v_pk_mul_f32 v[42:43], v[42:43], v[60:61] op_sel_hi:[1,0]
	v_pk_mul_f32 v[40:41], v[40:41], v[60:61] op_sel_hi:[1,0]
	v_pk_mul_f32 v[38:39], v[38:39], v[60:61] op_sel_hi:[1,0]
	v_pk_mul_f32 v[36:37], v[36:37], v[60:61] op_sel_hi:[1,0]
	v_pk_mul_f32 v[34:35], v[34:35], v[60:61] op_sel_hi:[1,0]
	v_pk_mul_f32 v[32:33], v[32:33], v[60:61] op_sel_hi:[1,0]
	s_branch .LBB0_1177
